# all loop-level reductions combined (chain sink, constant folding, immediate-offset reads, merged waits, static priority) incl. D/PLE loops and compare moved into the last MFMA segment
# baseline (speedup 1.0000x reference)
.LBB0_446:
	ds_read_b128 v[114:117], v243
	ds_read_b128 v[126:129], v243 offset:1024
	ds_read_b128 v[130:133], v243 offset:2048
	ds_read_b128 v[134:137], v243 offset:3072
	ds_read_b128 v[146:149], v243 offset:16384
	ds_read_b128 v[150:153], v243 offset:17408
	ds_read_b128 v[158:161], v243 offset:18432
	ds_read_b128 v[182:185], v243 offset:19456
	ds_read_b128 v[186:189], v193
	ds_read_b128 v[194:197], v193 offset:1024
	ds_read_b128 v[198:201], v193 offset:2048
	ds_read_b128 v[214:217], v193 offset:3072
	ds_read_b128 v[218:221], v193 offset:4096
	ds_read_b128 v[222:225], v193 offset:5120
	ds_read_b128 v[226:229], v193 offset:6144
	ds_read_b128 v[230:233], v193 offset:7168
	s_add_i32 m0, s47, 0xc000
	v_lshl_add_u64 v[162:163], s[56:57], 0, v[156:157]
	global_load_lds_dwordx4 v[162:163], off
	v_lshl_add_u64 v[162:163], v[162:163], 0, s[2:3]
	s_add_i32 m0, s47, 0xe000
	s_nop 0
	global_load_lds_dwordx4 v[162:163], off
	s_waitcnt vmcnt(8) lgkmcnt(0)
	s_barrier
	v_mfma_f32_16x16x32_bf16 v[142:145], v[114:117], v[186:189], v[142:145]
	v_mfma_f32_16x16x32_bf16 v[142:145], v[126:129], v[194:197], v[142:145]
	v_mfma_f32_16x16x32_bf16 v[138:141], v[130:133], v[186:189], v[138:141]
	v_mfma_f32_16x16x32_bf16 v[138:141], v[134:137], v[194:197], v[138:141]
	v_mfma_f32_16x16x32_bf16 v[110:113], v[114:117], v[198:201], v[110:113]
	v_mfma_f32_16x16x32_bf16 v[110:113], v[126:129], v[214:217], v[110:113]
	v_mfma_f32_16x16x32_bf16 v[106:109], v[130:133], v[198:201], v[106:109]
	v_mfma_f32_16x16x32_bf16 v[106:109], v[134:137], v[214:217], v[106:109]
	v_mfma_f32_16x16x32_bf16 v[94:97], v[114:117], v[218:221], v[94:97]
	v_mfma_f32_16x16x32_bf16 v[94:97], v[126:129], v[222:225], v[94:97]
	v_mfma_f32_16x16x32_bf16 v[90:93], v[130:133], v[218:221], v[90:93]
	v_mfma_f32_16x16x32_bf16 v[90:93], v[134:137], v[222:225], v[90:93]
	v_mfma_f32_16x16x32_bf16 v[78:81], v[114:117], v[226:229], v[78:81]
	v_mfma_f32_16x16x32_bf16 v[78:81], v[126:129], v[230:233], v[78:81]
	v_mfma_f32_16x16x32_bf16 v[74:77], v[130:133], v[226:229], v[74:77]
	v_mfma_f32_16x16x32_bf16 v[74:77], v[134:137], v[230:233], v[74:77]
	s_add_u32 s20, s56, 0xfff50080
	s_addc_u32 s21, s57, -1
	s_cmp_eq_u32 s84, 40
	s_cselect_b32 s61, s49, s21
	s_cselect_b32 s60, s48, s20
	s_cselect_b32 s21, s51, s63
	s_cselect_b32 s20, s50, s62
	v_mfma_f32_16x16x32_bf16 v[122:125], v[146:149], v[186:189], v[122:125]
	v_mfma_f32_16x16x32_bf16 v[122:125], v[150:153], v[194:197], v[122:125]
	v_mfma_f32_16x16x32_bf16 v[118:121], v[158:161], v[186:189], v[118:121]
	v_mfma_f32_16x16x32_bf16 v[118:121], v[182:185], v[194:197], v[118:121]
	v_mfma_f32_16x16x32_bf16 v[102:105], v[146:149], v[198:201], v[102:105]
	v_mfma_f32_16x16x32_bf16 v[102:105], v[150:153], v[214:217], v[102:105]
	v_mfma_f32_16x16x32_bf16 v[98:101], v[158:161], v[198:201], v[98:101]
	v_mfma_f32_16x16x32_bf16 v[98:101], v[182:185], v[214:217], v[98:101]
	v_mfma_f32_16x16x32_bf16 v[86:89], v[146:149], v[218:221], v[86:89]
	v_mfma_f32_16x16x32_bf16 v[86:89], v[150:153], v[222:225], v[86:89]
	v_mfma_f32_16x16x32_bf16 v[82:85], v[158:161], v[218:221], v[82:85]
	v_mfma_f32_16x16x32_bf16 v[82:85], v[182:185], v[222:225], v[82:85]
	v_mfma_f32_16x16x32_bf16 v[70:73], v[146:149], v[226:229], v[70:73]
	v_mfma_f32_16x16x32_bf16 v[70:73], v[150:153], v[230:233], v[70:73]
	v_mfma_f32_16x16x32_bf16 v[66:69], v[158:161], v[226:229], v[66:69]
	v_mfma_f32_16x16x32_bf16 v[66:69], v[182:185], v[230:233], v[66:69]
	s_barrier
	ds_read_b128 v[186:189], v193 offset:16384
	ds_read_b128 v[194:197], v193 offset:17408
	ds_read_b128 v[198:201], v193 offset:18432
	ds_read_b128 v[214:217], v193 offset:19456
	ds_read_b128 v[218:221], v193 offset:20480
	ds_read_b128 v[222:225], v193 offset:21504
	ds_read_b128 v[226:229], v193 offset:22528
	ds_read_b128 v[230:233], v193 offset:23552
	v_lshl_add_u64 v[162:163], s[20:21], 0, v[0:1]
	s_add_i32 s20, s46, 0x10000
	s_mov_b32 m0, s20
	s_nop 0
	s_nop 0
	global_load_lds_dwordx4 v[162:163], off
	v_lshl_add_u64 v[202:203], v[162:163], 0, s[2:3]
	s_add_i32 m0, s20, 0x2000
	s_add_i32 s20, s46, 0x14000
	global_load_lds_dwordx4 v[202:203], off
	v_lshl_add_u64 v[202:203], v[162:163], 0, s[12:13]
	s_mov_b32 m0, s20
	s_nop 0
	global_load_lds_dwordx4 v[202:203], off
	v_lshl_add_u64 v[202:203], v[162:163], 0, s[86:87]
	s_add_i32 m0, s20, 0x2000
	s_nop 0
	global_load_lds_dwordx4 v[202:203], off
	v_lshl_add_u64 v[202:203], s[60:61], 0, v[154:155]
	s_mov_b32 m0, s47
	v_lshl_add_u64 v[234:235], v[202:203], 0, s[2:3]
	global_load_lds_dwordx4 v[202:203], off
	s_mov_b32 m0, s68
	s_nop 0
	global_load_lds_dwordx4 v[234:235], off
	s_waitcnt vmcnt(8) lgkmcnt(0)
	s_barrier
	v_mfma_f32_16x16x32_bf16 v[62:65], v[114:117], v[186:189], v[62:65]
	v_mfma_f32_16x16x32_bf16 v[62:65], v[126:129], v[194:197], v[62:65]
	v_mfma_f32_16x16x32_bf16 v[58:61], v[130:133], v[186:189], v[58:61]
	v_mfma_f32_16x16x32_bf16 v[58:61], v[134:137], v[194:197], v[58:61]
	v_mfma_f32_16x16x32_bf16 v[46:49], v[114:117], v[198:201], v[46:49]
	v_mfma_f32_16x16x32_bf16 v[46:49], v[126:129], v[214:217], v[46:49]
	v_mfma_f32_16x16x32_bf16 v[42:45], v[130:133], v[198:201], v[42:45]
	v_mfma_f32_16x16x32_bf16 v[42:45], v[134:137], v[214:217], v[42:45]
	v_mfma_f32_16x16x32_bf16 v[30:33], v[114:117], v[218:221], v[30:33]
	v_mfma_f32_16x16x32_bf16 v[30:33], v[126:129], v[222:225], v[30:33]
	v_mfma_f32_16x16x32_bf16 v[26:29], v[130:133], v[218:221], v[26:29]
	v_mfma_f32_16x16x32_bf16 v[26:29], v[134:137], v[222:225], v[26:29]
	v_mfma_f32_16x16x32_bf16 v[14:17], v[114:117], v[226:229], v[14:17]
	v_mfma_f32_16x16x32_bf16 v[14:17], v[126:129], v[230:233], v[14:17]
	v_mfma_f32_16x16x32_bf16 v[10:13], v[130:133], v[226:229], v[10:13]
	v_mfma_f32_16x16x32_bf16 v[10:13], v[134:137], v[230:233], v[10:13]
	v_mfma_f32_16x16x32_bf16 v[54:57], v[146:149], v[186:189], v[54:57]
	v_mfma_f32_16x16x32_bf16 v[54:57], v[150:153], v[194:197], v[54:57]
	v_mfma_f32_16x16x32_bf16 v[50:53], v[158:161], v[186:189], v[50:53]
	v_mfma_f32_16x16x32_bf16 v[50:53], v[182:185], v[194:197], v[50:53]
	v_mfma_f32_16x16x32_bf16 v[38:41], v[146:149], v[198:201], v[38:41]
	v_mfma_f32_16x16x32_bf16 v[38:41], v[150:153], v[214:217], v[38:41]
	v_mfma_f32_16x16x32_bf16 v[34:37], v[158:161], v[198:201], v[34:37]
	v_mfma_f32_16x16x32_bf16 v[34:37], v[182:185], v[214:217], v[34:37]
	v_mfma_f32_16x16x32_bf16 v[22:25], v[146:149], v[218:221], v[22:25]
	v_mfma_f32_16x16x32_bf16 v[22:25], v[150:153], v[222:225], v[22:25]
	v_mfma_f32_16x16x32_bf16 v[18:21], v[158:161], v[218:221], v[18:21]
	v_mfma_f32_16x16x32_bf16 v[18:21], v[182:185], v[222:225], v[18:21]
	v_mfma_f32_16x16x32_bf16 v[6:9], v[146:149], v[226:229], v[6:9]
	v_mfma_f32_16x16x32_bf16 v[6:9], v[150:153], v[230:233], v[6:9]
	v_mfma_f32_16x16x32_bf16 v[2:5], v[158:161], v[226:229], v[2:5]
	v_mfma_f32_16x16x32_bf16 v[2:5], v[182:185], v[230:233], v[2:5]
	s_barrier
	ds_read_b128 v[114:117], v243 offset:32768
	ds_read_b128 v[126:129], v243 offset:33792
	ds_read_b128 v[130:133], v243 offset:34816
	ds_read_b128 v[134:137], v243 offset:35840
	ds_read_b128 v[146:149], v243 offset:49152
	ds_read_b128 v[150:153], v243 offset:50176
	ds_read_b128 v[158:161], v243 offset:51200
	ds_read_b128 v[182:185], v243 offset:52224
	ds_read_b128 v[186:189], v193 offset:32768
	ds_read_b128 v[194:197], v193 offset:33792
	ds_read_b128 v[198:201], v193 offset:34816
	ds_read_b128 v[214:217], v193 offset:35840
	ds_read_b128 v[218:221], v193 offset:36864
	ds_read_b128 v[222:225], v193 offset:37888
	ds_read_b128 v[226:229], v193 offset:38912
	ds_read_b128 v[230:233], v193 offset:39936
	s_mov_b32 m0, s69
	v_lshl_add_u64 v[234:235], v[202:203], 0, s[12:13]
	global_load_lds_dwordx4 v[234:235], off
	v_lshl_add_u64 v[234:235], v[202:203], 0, s[86:87]
	s_mov_b32 m0, s76
	s_nop 0
	global_load_lds_dwordx4 v[234:235], off
	s_waitcnt vmcnt(8) lgkmcnt(0)
	s_barrier
	v_mfma_f32_16x16x32_bf16 v[142:145], v[114:117], v[186:189], v[142:145]
	v_mfma_f32_16x16x32_bf16 v[142:145], v[126:129], v[194:197], v[142:145]
	v_mfma_f32_16x16x32_bf16 v[138:141], v[130:133], v[186:189], v[138:141]
	v_mfma_f32_16x16x32_bf16 v[138:141], v[134:137], v[194:197], v[138:141]
	v_mfma_f32_16x16x32_bf16 v[110:113], v[114:117], v[198:201], v[110:113]
	v_mfma_f32_16x16x32_bf16 v[110:113], v[126:129], v[214:217], v[110:113]
	v_mfma_f32_16x16x32_bf16 v[106:109], v[130:133], v[198:201], v[106:109]
	v_mfma_f32_16x16x32_bf16 v[106:109], v[134:137], v[214:217], v[106:109]
	v_mfma_f32_16x16x32_bf16 v[94:97], v[114:117], v[218:221], v[94:97]
	v_mfma_f32_16x16x32_bf16 v[94:97], v[126:129], v[222:225], v[94:97]
	v_mfma_f32_16x16x32_bf16 v[90:93], v[130:133], v[218:221], v[90:93]
	v_mfma_f32_16x16x32_bf16 v[90:93], v[134:137], v[222:225], v[90:93]
	v_mfma_f32_16x16x32_bf16 v[78:81], v[114:117], v[226:229], v[78:81]
	v_mfma_f32_16x16x32_bf16 v[78:81], v[126:129], v[230:233], v[78:81]
	v_mfma_f32_16x16x32_bf16 v[74:77], v[130:133], v[226:229], v[74:77]
	v_mfma_f32_16x16x32_bf16 v[74:77], v[134:137], v[230:233], v[74:77]
	v_mfma_f32_16x16x32_bf16 v[122:125], v[146:149], v[186:189], v[122:125]
	v_mfma_f32_16x16x32_bf16 v[122:125], v[150:153], v[194:197], v[122:125]
	v_mfma_f32_16x16x32_bf16 v[118:121], v[158:161], v[186:189], v[118:121]
	v_mfma_f32_16x16x32_bf16 v[118:121], v[182:185], v[194:197], v[118:121]
	v_mfma_f32_16x16x32_bf16 v[102:105], v[146:149], v[198:201], v[102:105]
	v_mfma_f32_16x16x32_bf16 v[102:105], v[150:153], v[214:217], v[102:105]
	v_mfma_f32_16x16x32_bf16 v[98:101], v[158:161], v[198:201], v[98:101]
	v_mfma_f32_16x16x32_bf16 v[98:101], v[182:185], v[214:217], v[98:101]
	v_mfma_f32_16x16x32_bf16 v[86:89], v[146:149], v[218:221], v[86:89]
	v_mfma_f32_16x16x32_bf16 v[86:89], v[150:153], v[222:225], v[86:89]
	v_mfma_f32_16x16x32_bf16 v[82:85], v[158:161], v[218:221], v[82:85]
	v_mfma_f32_16x16x32_bf16 v[82:85], v[182:185], v[222:225], v[82:85]
	v_mfma_f32_16x16x32_bf16 v[70:73], v[146:149], v[226:229], v[70:73]
	v_mfma_f32_16x16x32_bf16 v[70:73], v[150:153], v[230:233], v[70:73]
	v_mfma_f32_16x16x32_bf16 v[66:69], v[158:161], v[226:229], v[66:69]
	v_mfma_f32_16x16x32_bf16 v[66:69], v[182:185], v[230:233], v[66:69]
	s_barrier
	ds_read_b128 v[186:189], v193 offset:49152
	ds_read_b128 v[194:197], v193 offset:50176
	ds_read_b128 v[198:201], v193 offset:51200
	ds_read_b128 v[214:217], v193 offset:52224
	ds_read_b128 v[218:221], v193 offset:53248
	ds_read_b128 v[222:225], v193 offset:54272
	ds_read_b128 v[226:229], v193 offset:55296
	ds_read_b128 v[230:233], v193 offset:56320
	s_add_i32 s20, s46, 0x18000
	s_mov_b32 m0, s20
	v_lshl_add_u64 v[234:235], v[162:163], 0, s[34:35]
	global_load_lds_dwordx4 v[234:235], off
	v_lshl_add_u64 v[234:235], v[162:163], 0, s[96:97]
	s_add_i32 m0, s20, 0x2000
	s_add_i32 s20, s46, 0x1c000
	global_load_lds_dwordx4 v[234:235], off
	v_lshl_add_u64 v[234:235], v[162:163], 0, vcc
	s_mov_b32 m0, s20
	v_lshl_add_u64 v[162:163], v[162:163], 0, s[0:1]
	global_load_lds_dwordx4 v[234:235], off
	s_add_i32 m0, s20, 0x2000
	s_nop 0
	global_load_lds_dwordx4 v[162:163], off
	v_lshl_add_u64 v[162:163], v[202:203], 0, s[34:35]
	s_mov_b32 m0, s77
	s_nop 0
	global_load_lds_dwordx4 v[162:163], off
	v_lshl_add_u64 v[162:163], v[202:203], 0, s[96:97]
	s_mov_b32 m0, s78
	s_nop 0
	global_load_lds_dwordx4 v[162:163], off
	s_waitcnt vmcnt(8) lgkmcnt(0)
	s_barrier
	v_mfma_f32_16x16x32_bf16 v[62:65], v[114:117], v[186:189], v[62:65]
	v_mfma_f32_16x16x32_bf16 v[62:65], v[126:129], v[194:197], v[62:65]
	v_mfma_f32_16x16x32_bf16 v[58:61], v[130:133], v[186:189], v[58:61]
	v_mfma_f32_16x16x32_bf16 v[58:61], v[134:137], v[194:197], v[58:61]
	v_mfma_f32_16x16x32_bf16 v[46:49], v[114:117], v[198:201], v[46:49]
	v_mfma_f32_16x16x32_bf16 v[46:49], v[126:129], v[214:217], v[46:49]
	v_mfma_f32_16x16x32_bf16 v[42:45], v[130:133], v[198:201], v[42:45]
	v_mfma_f32_16x16x32_bf16 v[42:45], v[134:137], v[214:217], v[42:45]
	v_mfma_f32_16x16x32_bf16 v[30:33], v[114:117], v[218:221], v[30:33]
	v_mfma_f32_16x16x32_bf16 v[30:33], v[126:129], v[222:225], v[30:33]
	v_mfma_f32_16x16x32_bf16 v[26:29], v[130:133], v[218:221], v[26:29]
	v_mfma_f32_16x16x32_bf16 v[26:29], v[134:137], v[222:225], v[26:29]
	v_mfma_f32_16x16x32_bf16 v[14:17], v[114:117], v[226:229], v[14:17]
	v_mfma_f32_16x16x32_bf16 v[14:17], v[126:129], v[230:233], v[14:17]
	v_mfma_f32_16x16x32_bf16 v[10:13], v[130:133], v[226:229], v[10:13]
	v_mfma_f32_16x16x32_bf16 v[10:13], v[134:137], v[230:233], v[10:13]
	s_add_i32 s84, s84, 2
	s_add_u32 s56, s56, 0x100
	s_addc_u32 s57, s57, 0
	s_add_u32 s62, s62, 0x100
	s_addc_u32 s63, s63, 0
	s_cmp_gt_u32 s84, 41
	v_mfma_f32_16x16x32_bf16 v[54:57], v[146:149], v[186:189], v[54:57]
	v_mfma_f32_16x16x32_bf16 v[54:57], v[150:153], v[194:197], v[54:57]
	v_mfma_f32_16x16x32_bf16 v[50:53], v[158:161], v[186:189], v[50:53]
	v_mfma_f32_16x16x32_bf16 v[50:53], v[182:185], v[194:197], v[50:53]
	v_mfma_f32_16x16x32_bf16 v[38:41], v[146:149], v[198:201], v[38:41]
	v_mfma_f32_16x16x32_bf16 v[38:41], v[150:153], v[214:217], v[38:41]
	v_mfma_f32_16x16x32_bf16 v[34:37], v[158:161], v[198:201], v[34:37]
	v_mfma_f32_16x16x32_bf16 v[34:37], v[182:185], v[214:217], v[34:37]
	v_mfma_f32_16x16x32_bf16 v[22:25], v[146:149], v[218:221], v[22:25]
	v_mfma_f32_16x16x32_bf16 v[22:25], v[150:153], v[222:225], v[22:25]
	v_mfma_f32_16x16x32_bf16 v[18:21], v[158:161], v[218:221], v[18:21]
	v_mfma_f32_16x16x32_bf16 v[18:21], v[182:185], v[222:225], v[18:21]
	v_mfma_f32_16x16x32_bf16 v[6:9], v[146:149], v[226:229], v[6:9]
	v_mfma_f32_16x16x32_bf16 v[6:9], v[150:153], v[230:233], v[6:9]
	v_mfma_f32_16x16x32_bf16 v[2:5], v[158:161], v[226:229], v[2:5]
	v_mfma_f32_16x16x32_bf16 v[2:5], v[182:185], v[230:233], v[2:5]
	s_barrier
	s_cbranch_scc0 .LBB0_446
	s_setprio 0
	s_and_b64 vcc, exec, s[40:41]
	s_cbranch_vccz .LBB0_449
	s_barrier

.LBB0_488:
	ds_read_b128 v[134:137], v243
	ds_read_b128 v[144:147], v243 offset:1024
	ds_read_b128 v[148:151], v243 offset:2048
	ds_read_b128 v[152:155], v243 offset:3072
	ds_read_b128 v[156:159], v243 offset:16384
	ds_read_b128 v[160:163], v243 offset:17408
	ds_read_b128 v[182:185], v243 offset:18432
	ds_read_b128 v[186:189], v243 offset:19456
	ds_read_b128 v[190:193], v142
	ds_read_b128 v[194:197], v142 offset:1024
	ds_read_b128 v[198:201], v142 offset:2048
	ds_read_b128 v[214:217], v142 offset:3072
	ds_read_b128 v[218:221], v142 offset:4096
	ds_read_b128 v[222:225], v142 offset:5120
	ds_read_b128 v[226:229], v142 offset:6144
	ds_read_b128 v[230:233], v142 offset:7168
	s_add_i32 m0, s43, 0xc000
	v_lshl_add_u64 v[202:203], s[68:69], 0, v[132:133]
	global_load_lds_dwordx4 v[202:203], off
	v_lshl_add_u64 v[202:203], v[202:203], 0, s[72:73]
	s_add_i32 m0, s43, 0xe000
	s_nop 0
	global_load_lds_dwordx4 v[202:203], off
	s_waitcnt vmcnt(8) lgkmcnt(0)
	s_barrier
	v_mfma_f32_16x16x32_bf16 v[126:129], v[134:137], v[190:193], v[126:129]
	v_mfma_f32_16x16x32_bf16 v[126:129], v[144:147], v[194:197], v[126:129]
	v_mfma_f32_16x16x32_bf16 v[114:117], v[148:151], v[190:193], v[114:117]
	v_mfma_f32_16x16x32_bf16 v[114:117], v[152:155], v[194:197], v[114:117]
	v_mfma_f32_16x16x32_bf16 v[110:113], v[134:137], v[198:201], v[110:113]
	v_mfma_f32_16x16x32_bf16 v[110:113], v[144:147], v[214:217], v[110:113]
	v_mfma_f32_16x16x32_bf16 v[98:101], v[148:151], v[198:201], v[98:101]
	v_mfma_f32_16x16x32_bf16 v[98:101], v[152:155], v[214:217], v[98:101]
	v_mfma_f32_16x16x32_bf16 v[94:97], v[134:137], v[218:221], v[94:97]
	v_mfma_f32_16x16x32_bf16 v[94:97], v[144:147], v[222:225], v[94:97]
	v_mfma_f32_16x16x32_bf16 v[82:85], v[148:151], v[218:221], v[82:85]
	v_mfma_f32_16x16x32_bf16 v[82:85], v[152:155], v[222:225], v[82:85]
	v_mfma_f32_16x16x32_bf16 v[78:81], v[134:137], v[226:229], v[78:81]
	v_mfma_f32_16x16x32_bf16 v[78:81], v[144:147], v[230:233], v[78:81]
	v_mfma_f32_16x16x32_bf16 v[66:69], v[148:151], v[226:229], v[66:69]
	v_mfma_f32_16x16x32_bf16 v[66:69], v[152:155], v[230:233], v[66:69]
	s_add_u32 s20, s68, 0xfffc0080
	s_addc_u32 s21, s69, -1
	s_cmp_eq_u32 s97, 12
	s_cselect_b32 s77, s57, s21
	s_cselect_b32 s76, s86, s20
	s_cselect_b32 s21, s51, s96
	s_cselect_b32 s20, s87, s91
	v_mfma_f32_16x16x32_bf16 v[122:125], v[156:159], v[190:193], v[122:125]
	v_mfma_f32_16x16x32_bf16 v[122:125], v[160:163], v[194:197], v[122:125]
	v_mfma_f32_16x16x32_bf16 v[118:121], v[182:185], v[190:193], v[118:121]
	v_mfma_f32_16x16x32_bf16 v[118:121], v[186:189], v[194:197], v[118:121]
	v_mfma_f32_16x16x32_bf16 v[106:109], v[156:159], v[198:201], v[106:109]
	v_mfma_f32_16x16x32_bf16 v[106:109], v[160:163], v[214:217], v[106:109]
	v_mfma_f32_16x16x32_bf16 v[102:105], v[182:185], v[198:201], v[102:105]
	v_mfma_f32_16x16x32_bf16 v[102:105], v[186:189], v[214:217], v[102:105]
	v_mfma_f32_16x16x32_bf16 v[90:93], v[156:159], v[218:221], v[90:93]
	v_mfma_f32_16x16x32_bf16 v[90:93], v[160:163], v[222:225], v[90:93]
	v_mfma_f32_16x16x32_bf16 v[86:89], v[182:185], v[218:221], v[86:89]
	v_mfma_f32_16x16x32_bf16 v[86:89], v[186:189], v[222:225], v[86:89]
	v_mfma_f32_16x16x32_bf16 v[74:77], v[156:159], v[226:229], v[74:77]
	v_mfma_f32_16x16x32_bf16 v[74:77], v[160:163], v[230:233], v[74:77]
	v_mfma_f32_16x16x32_bf16 v[70:73], v[182:185], v[226:229], v[70:73]
	v_mfma_f32_16x16x32_bf16 v[70:73], v[186:189], v[230:233], v[70:73]
	s_barrier
	ds_read_b128 v[190:193], v142 offset:16384
	ds_read_b128 v[194:197], v142 offset:17408
	ds_read_b128 v[198:201], v142 offset:18432
	ds_read_b128 v[214:217], v142 offset:19456
	ds_read_b128 v[218:221], v142 offset:20480
	ds_read_b128 v[222:225], v142 offset:21504
	ds_read_b128 v[226:229], v142 offset:22528
	ds_read_b128 v[230:233], v142 offset:23552
	v_lshl_add_u64 v[202:203], s[20:21], 0, v[0:1]
	s_add_i32 s20, s14, 0x10000
	s_mov_b32 m0, s20
	s_nop 0
	s_nop 0
	global_load_lds_dwordx4 v[202:203], off
	v_lshl_add_u64 v[234:235], v[202:203], 0, s[72:73]
	s_add_i32 m0, s20, 0x2000
	s_add_i32 s20, s14, 0x14000
	global_load_lds_dwordx4 v[234:235], off
	v_lshl_add_u64 v[234:235], v[202:203], 0, s[28:29]
	s_mov_b32 m0, s20
	s_nop 0
	global_load_lds_dwordx4 v[234:235], off
	v_lshl_add_u64 v[234:235], v[202:203], 0, s[82:83]
	s_add_i32 m0, s20, 0x2000
	s_nop 0
	global_load_lds_dwordx4 v[234:235], off
	v_lshl_add_u64 v[234:235], s[76:77], 0, v[130:131]
	s_mov_b32 m0, s43
	v_lshl_add_u64 v[236:237], v[234:235], 0, s[72:73]
	global_load_lds_dwordx4 v[234:235], off
	s_mov_b32 m0, s46
	s_nop 0
	global_load_lds_dwordx4 v[236:237], off
	s_waitcnt vmcnt(8) lgkmcnt(0)
	s_barrier
	v_mfma_f32_16x16x32_bf16 v[62:65], v[134:137], v[190:193], v[62:65]
	v_mfma_f32_16x16x32_bf16 v[62:65], v[144:147], v[194:197], v[62:65]
	v_mfma_f32_16x16x32_bf16 v[50:53], v[148:151], v[190:193], v[50:53]
	v_mfma_f32_16x16x32_bf16 v[50:53], v[152:155], v[194:197], v[50:53]
	v_mfma_f32_16x16x32_bf16 v[46:49], v[134:137], v[198:201], v[46:49]
	v_mfma_f32_16x16x32_bf16 v[46:49], v[144:147], v[214:217], v[46:49]
	v_mfma_f32_16x16x32_bf16 v[34:37], v[148:151], v[198:201], v[34:37]
	v_mfma_f32_16x16x32_bf16 v[34:37], v[152:155], v[214:217], v[34:37]
	v_mfma_f32_16x16x32_bf16 v[30:33], v[134:137], v[218:221], v[30:33]
	v_mfma_f32_16x16x32_bf16 v[30:33], v[144:147], v[222:225], v[30:33]
	v_mfma_f32_16x16x32_bf16 v[18:21], v[148:151], v[218:221], v[18:21]
	v_mfma_f32_16x16x32_bf16 v[18:21], v[152:155], v[222:225], v[18:21]
	v_mfma_f32_16x16x32_bf16 v[14:17], v[134:137], v[226:229], v[14:17]
	v_mfma_f32_16x16x32_bf16 v[14:17], v[144:147], v[230:233], v[14:17]
	v_mfma_f32_16x16x32_bf16 v[6:9], v[148:151], v[226:229], v[6:9]
	v_mfma_f32_16x16x32_bf16 v[6:9], v[152:155], v[230:233], v[6:9]
	v_mfma_f32_16x16x32_bf16 v[58:61], v[156:159], v[190:193], v[58:61]
	v_mfma_f32_16x16x32_bf16 v[58:61], v[160:163], v[194:197], v[58:61]
	v_mfma_f32_16x16x32_bf16 v[54:57], v[182:185], v[190:193], v[54:57]
	v_mfma_f32_16x16x32_bf16 v[54:57], v[186:189], v[194:197], v[54:57]
	v_mfma_f32_16x16x32_bf16 v[42:45], v[156:159], v[198:201], v[42:45]
	v_mfma_f32_16x16x32_bf16 v[42:45], v[160:163], v[214:217], v[42:45]
	v_mfma_f32_16x16x32_bf16 v[38:41], v[182:185], v[198:201], v[38:41]
	v_mfma_f32_16x16x32_bf16 v[38:41], v[186:189], v[214:217], v[38:41]
	v_mfma_f32_16x16x32_bf16 v[26:29], v[156:159], v[218:221], v[26:29]
	v_mfma_f32_16x16x32_bf16 v[26:29], v[160:163], v[222:225], v[26:29]
	v_mfma_f32_16x16x32_bf16 v[22:25], v[182:185], v[218:221], v[22:25]
	v_mfma_f32_16x16x32_bf16 v[22:25], v[186:189], v[222:225], v[22:25]
	v_mfma_f32_16x16x32_bf16 v[10:13], v[156:159], v[226:229], v[10:13]
	v_mfma_f32_16x16x32_bf16 v[10:13], v[160:163], v[230:233], v[10:13]
	v_mfma_f32_16x16x32_bf16 v[2:5], v[182:185], v[226:229], v[2:5]
	v_mfma_f32_16x16x32_bf16 v[2:5], v[186:189], v[230:233], v[2:5]
	s_barrier
	ds_read_b128 v[134:137], v243 offset:32768
	ds_read_b128 v[144:147], v243 offset:33792
	ds_read_b128 v[148:151], v243 offset:34816
	ds_read_b128 v[152:155], v243 offset:35840
	ds_read_b128 v[156:159], v243 offset:49152
	ds_read_b128 v[160:163], v243 offset:50176
	ds_read_b128 v[182:185], v243 offset:51200
	ds_read_b128 v[186:189], v243 offset:52224
	ds_read_b128 v[190:193], v142 offset:32768
	ds_read_b128 v[194:197], v142 offset:33792
	ds_read_b128 v[198:201], v142 offset:34816
	ds_read_b128 v[214:217], v142 offset:35840
	ds_read_b128 v[218:221], v142 offset:36864
	ds_read_b128 v[222:225], v142 offset:37888
	ds_read_b128 v[226:229], v142 offset:38912
	ds_read_b128 v[230:233], v142 offset:39936
	s_mov_b32 m0, s47
	v_lshl_add_u64 v[236:237], v[234:235], 0, s[28:29]
	global_load_lds_dwordx4 v[236:237], off
	v_lshl_add_u64 v[236:237], v[234:235], 0, s[82:83]
	s_mov_b32 m0, s78
	s_nop 0
	global_load_lds_dwordx4 v[236:237], off
	s_waitcnt vmcnt(8) lgkmcnt(0)
	s_barrier
	v_mfma_f32_16x16x32_bf16 v[126:129], v[134:137], v[190:193], v[126:129]
	v_mfma_f32_16x16x32_bf16 v[126:129], v[144:147], v[194:197], v[126:129]
	v_mfma_f32_16x16x32_bf16 v[114:117], v[148:151], v[190:193], v[114:117]
	v_mfma_f32_16x16x32_bf16 v[114:117], v[152:155], v[194:197], v[114:117]
	v_mfma_f32_16x16x32_bf16 v[110:113], v[134:137], v[198:201], v[110:113]
	v_mfma_f32_16x16x32_bf16 v[110:113], v[144:147], v[214:217], v[110:113]
	v_mfma_f32_16x16x32_bf16 v[98:101], v[148:151], v[198:201], v[98:101]
	v_mfma_f32_16x16x32_bf16 v[98:101], v[152:155], v[214:217], v[98:101]
	v_mfma_f32_16x16x32_bf16 v[94:97], v[134:137], v[218:221], v[94:97]
	v_mfma_f32_16x16x32_bf16 v[94:97], v[144:147], v[222:225], v[94:97]
	v_mfma_f32_16x16x32_bf16 v[82:85], v[148:151], v[218:221], v[82:85]
	v_mfma_f32_16x16x32_bf16 v[82:85], v[152:155], v[222:225], v[82:85]
	v_mfma_f32_16x16x32_bf16 v[78:81], v[134:137], v[226:229], v[78:81]
	v_mfma_f32_16x16x32_bf16 v[78:81], v[144:147], v[230:233], v[78:81]
	v_mfma_f32_16x16x32_bf16 v[66:69], v[148:151], v[226:229], v[66:69]
	v_mfma_f32_16x16x32_bf16 v[66:69], v[152:155], v[230:233], v[66:69]
	v_mfma_f32_16x16x32_bf16 v[122:125], v[156:159], v[190:193], v[122:125]
	v_mfma_f32_16x16x32_bf16 v[122:125], v[160:163], v[194:197], v[122:125]
	v_mfma_f32_16x16x32_bf16 v[118:121], v[182:185], v[190:193], v[118:121]
	v_mfma_f32_16x16x32_bf16 v[118:121], v[186:189], v[194:197], v[118:121]
	v_mfma_f32_16x16x32_bf16 v[106:109], v[156:159], v[198:201], v[106:109]
	v_mfma_f32_16x16x32_bf16 v[106:109], v[160:163], v[214:217], v[106:109]
	v_mfma_f32_16x16x32_bf16 v[102:105], v[182:185], v[198:201], v[102:105]
	v_mfma_f32_16x16x32_bf16 v[102:105], v[186:189], v[214:217], v[102:105]
	v_mfma_f32_16x16x32_bf16 v[90:93], v[156:159], v[218:221], v[90:93]
	v_mfma_f32_16x16x32_bf16 v[90:93], v[160:163], v[222:225], v[90:93]
	v_mfma_f32_16x16x32_bf16 v[86:89], v[182:185], v[218:221], v[86:89]
	v_mfma_f32_16x16x32_bf16 v[86:89], v[186:189], v[222:225], v[86:89]
	v_mfma_f32_16x16x32_bf16 v[74:77], v[156:159], v[226:229], v[74:77]
	v_mfma_f32_16x16x32_bf16 v[74:77], v[160:163], v[230:233], v[74:77]
	v_mfma_f32_16x16x32_bf16 v[70:73], v[182:185], v[226:229], v[70:73]
	v_mfma_f32_16x16x32_bf16 v[70:73], v[186:189], v[230:233], v[70:73]
	s_barrier
	ds_read_b128 v[190:193], v142 offset:49152
	ds_read_b128 v[194:197], v142 offset:50176
	ds_read_b128 v[198:201], v142 offset:51200
	ds_read_b128 v[214:217], v142 offset:52224
	ds_read_b128 v[218:221], v142 offset:53248
	ds_read_b128 v[222:225], v142 offset:54272
	ds_read_b128 v[226:229], v142 offset:55296
	ds_read_b128 v[230:233], v142 offset:56320
	s_add_i32 s20, s14, 0x18000
	s_mov_b32 m0, s20
	v_lshl_add_u64 v[236:237], v[202:203], 0, s[34:35]
	global_load_lds_dwordx4 v[236:237], off
	v_lshl_add_u64 v[236:237], v[202:203], 0, s[38:39]
	s_add_i32 m0, s20, 0x2000
	s_add_i32 s20, s14, 0x1c000
	global_load_lds_dwordx4 v[236:237], off
	v_lshl_add_u64 v[236:237], v[202:203], 0, s[44:45]
	s_mov_b32 m0, s20
	v_lshl_add_u64 v[202:203], v[202:203], 0, s[10:11]
	global_load_lds_dwordx4 v[236:237], off
	s_add_i32 m0, s20, 0x2000
	s_nop 0
	global_load_lds_dwordx4 v[202:203], off
	v_lshl_add_u64 v[202:203], v[234:235], 0, s[34:35]
	s_mov_b32 m0, s79
	s_nop 0
	global_load_lds_dwordx4 v[202:203], off
	v_lshl_add_u64 v[202:203], v[234:235], 0, s[38:39]
	s_mov_b32 m0, s88
	s_nop 0
	global_load_lds_dwordx4 v[202:203], off
	s_waitcnt vmcnt(8) lgkmcnt(0)
	s_barrier
	v_mfma_f32_16x16x32_bf16 v[62:65], v[134:137], v[190:193], v[62:65]
	v_mfma_f32_16x16x32_bf16 v[62:65], v[144:147], v[194:197], v[62:65]
	v_mfma_f32_16x16x32_bf16 v[50:53], v[148:151], v[190:193], v[50:53]
	v_mfma_f32_16x16x32_bf16 v[50:53], v[152:155], v[194:197], v[50:53]
	v_mfma_f32_16x16x32_bf16 v[46:49], v[134:137], v[198:201], v[46:49]
	v_mfma_f32_16x16x32_bf16 v[46:49], v[144:147], v[214:217], v[46:49]
	v_mfma_f32_16x16x32_bf16 v[34:37], v[148:151], v[198:201], v[34:37]
	v_mfma_f32_16x16x32_bf16 v[34:37], v[152:155], v[214:217], v[34:37]
	v_mfma_f32_16x16x32_bf16 v[30:33], v[134:137], v[218:221], v[30:33]
	v_mfma_f32_16x16x32_bf16 v[30:33], v[144:147], v[222:225], v[30:33]
	v_mfma_f32_16x16x32_bf16 v[18:21], v[148:151], v[218:221], v[18:21]
	v_mfma_f32_16x16x32_bf16 v[18:21], v[152:155], v[222:225], v[18:21]
	v_mfma_f32_16x16x32_bf16 v[14:17], v[134:137], v[226:229], v[14:17]
	v_mfma_f32_16x16x32_bf16 v[14:17], v[144:147], v[230:233], v[14:17]
	v_mfma_f32_16x16x32_bf16 v[6:9], v[148:151], v[226:229], v[6:9]
	v_mfma_f32_16x16x32_bf16 v[6:9], v[152:155], v[230:233], v[6:9]
	s_add_i32 s97, s97, 2
	s_add_u32 s68, s68, 0x100
	s_addc_u32 s69, s69, 0
	s_add_u32 s91, s91, 0x100
	s_addc_u32 s96, s96, 0
	s_cmp_gt_u32 s97, 13
	v_mfma_f32_16x16x32_bf16 v[58:61], v[156:159], v[190:193], v[58:61]
	v_mfma_f32_16x16x32_bf16 v[58:61], v[160:163], v[194:197], v[58:61]
	v_mfma_f32_16x16x32_bf16 v[54:57], v[182:185], v[190:193], v[54:57]
	v_mfma_f32_16x16x32_bf16 v[54:57], v[186:189], v[194:197], v[54:57]
	v_mfma_f32_16x16x32_bf16 v[42:45], v[156:159], v[198:201], v[42:45]
	v_mfma_f32_16x16x32_bf16 v[42:45], v[160:163], v[214:217], v[42:45]
	v_mfma_f32_16x16x32_bf16 v[38:41], v[182:185], v[198:201], v[38:41]
	v_mfma_f32_16x16x32_bf16 v[38:41], v[186:189], v[214:217], v[38:41]
	v_mfma_f32_16x16x32_bf16 v[26:29], v[156:159], v[218:221], v[26:29]
	v_mfma_f32_16x16x32_bf16 v[26:29], v[160:163], v[222:225], v[26:29]
	v_mfma_f32_16x16x32_bf16 v[22:25], v[182:185], v[218:221], v[22:25]
	v_mfma_f32_16x16x32_bf16 v[22:25], v[186:189], v[222:225], v[22:25]
	v_mfma_f32_16x16x32_bf16 v[10:13], v[156:159], v[226:229], v[10:13]
	v_mfma_f32_16x16x32_bf16 v[10:13], v[160:163], v[230:233], v[10:13]
	v_mfma_f32_16x16x32_bf16 v[2:5], v[182:185], v[226:229], v[2:5]
	v_mfma_f32_16x16x32_bf16 v[2:5], v[186:189], v[230:233], v[2:5]
	s_barrier
	s_cbranch_scc0 .LBB0_488
	s_setprio 0
	s_and_b64 vcc, exec, s[48:49]
	s_cbranch_vccz .LBB0_491
	s_barrier

.LBB0_604:
	ds_read_b128 v[134:137], v243
	ds_read_b128 v[142:145], v243 offset:1024
	ds_read_b128 v[146:149], v243 offset:2048
	ds_read_b128 v[150:153], v243 offset:3072
	ds_read_b128 v[154:157], v243 offset:16384
	ds_read_b128 v[158:161], v243 offset:17408
	ds_read_b128 v[182:185], v243 offset:18432
	ds_read_b128 v[186:189], v243 offset:19456
	ds_read_b128 v[190:193], v141
	ds_read_b128 v[194:197], v141 offset:1024
	ds_read_b128 v[198:201], v141 offset:2048
	ds_read_b128 v[214:217], v141 offset:3072
	ds_read_b128 v[218:221], v141 offset:4096
	ds_read_b128 v[222:225], v141 offset:5120
	ds_read_b128 v[226:229], v141 offset:6144
	ds_read_b128 v[230:233], v141 offset:7168
	s_add_i32 m0, s89, 0xc000
	v_lshl_add_u64 v[162:163], s[6:7], 0, v[132:133]
	global_load_lds_dwordx4 v[162:163], off
	v_lshl_add_u64 v[162:163], v[162:163], 0, s[64:65]
	s_add_i32 m0, s89, 0xe000
	s_nop 0
	global_load_lds_dwordx4 v[162:163], off
	s_waitcnt vmcnt(8) lgkmcnt(0)
	s_barrier
	v_mfma_f32_16x16x32_bf16 v[126:129], v[134:137], v[190:193], v[126:129]
	v_mfma_f32_16x16x32_bf16 v[126:129], v[142:145], v[194:197], v[126:129]
	v_mfma_f32_16x16x32_bf16 v[122:125], v[146:149], v[190:193], v[122:125]
	v_mfma_f32_16x16x32_bf16 v[122:125], v[150:153], v[194:197], v[122:125]
	v_mfma_f32_16x16x32_bf16 v[110:113], v[134:137], v[198:201], v[110:113]
	v_mfma_f32_16x16x32_bf16 v[110:113], v[142:145], v[214:217], v[110:113]
	v_mfma_f32_16x16x32_bf16 v[106:109], v[146:149], v[198:201], v[106:109]
	v_mfma_f32_16x16x32_bf16 v[106:109], v[150:153], v[214:217], v[106:109]
	v_mfma_f32_16x16x32_bf16 v[94:97], v[134:137], v[218:221], v[94:97]
	v_mfma_f32_16x16x32_bf16 v[94:97], v[142:145], v[222:225], v[94:97]
	v_mfma_f32_16x16x32_bf16 v[90:93], v[146:149], v[218:221], v[90:93]
	v_mfma_f32_16x16x32_bf16 v[90:93], v[150:153], v[222:225], v[90:93]
	v_mfma_f32_16x16x32_bf16 v[78:81], v[134:137], v[226:229], v[78:81]
	v_mfma_f32_16x16x32_bf16 v[78:81], v[142:145], v[230:233], v[78:81]
	v_mfma_f32_16x16x32_bf16 v[74:77], v[146:149], v[226:229], v[74:77]
	v_mfma_f32_16x16x32_bf16 v[74:77], v[150:153], v[230:233], v[74:77]
	s_add_u32 s20, s6, 0xfffe0080
	s_addc_u32 s21, s7, -1
	s_cmp_eq_u32 s84, 4
	s_cselect_b32 s69, s42, s21
	s_cselect_b32 s68, s43, s20
	s_cselect_b32 s21, s46, s51
	s_cselect_b32 s20, s47, s49
	v_mfma_f32_16x16x32_bf16 v[118:121], v[154:157], v[190:193], v[118:121]
	v_mfma_f32_16x16x32_bf16 v[118:121], v[158:161], v[194:197], v[118:121]
	v_mfma_f32_16x16x32_bf16 v[114:117], v[182:185], v[190:193], v[114:117]
	v_mfma_f32_16x16x32_bf16 v[114:117], v[186:189], v[194:197], v[114:117]
	v_mfma_f32_16x16x32_bf16 v[102:105], v[154:157], v[198:201], v[102:105]
	v_mfma_f32_16x16x32_bf16 v[102:105], v[158:161], v[214:217], v[102:105]
	v_mfma_f32_16x16x32_bf16 v[98:101], v[182:185], v[198:201], v[98:101]
	v_mfma_f32_16x16x32_bf16 v[98:101], v[186:189], v[214:217], v[98:101]
	v_mfma_f32_16x16x32_bf16 v[86:89], v[154:157], v[218:221], v[86:89]
	v_mfma_f32_16x16x32_bf16 v[86:89], v[158:161], v[222:225], v[86:89]
	v_mfma_f32_16x16x32_bf16 v[82:85], v[182:185], v[218:221], v[82:85]
	v_mfma_f32_16x16x32_bf16 v[82:85], v[186:189], v[222:225], v[82:85]
	v_mfma_f32_16x16x32_bf16 v[70:73], v[154:157], v[226:229], v[70:73]
	v_mfma_f32_16x16x32_bf16 v[70:73], v[158:161], v[230:233], v[70:73]
	v_mfma_f32_16x16x32_bf16 v[66:69], v[182:185], v[226:229], v[66:69]
	v_mfma_f32_16x16x32_bf16 v[66:69], v[186:189], v[230:233], v[66:69]
	s_barrier
	ds_read_b128 v[190:193], v141 offset:16384
	ds_read_b128 v[194:197], v141 offset:17408
	ds_read_b128 v[198:201], v141 offset:18432
	ds_read_b128 v[214:217], v141 offset:19456
	ds_read_b128 v[218:221], v141 offset:20480
	ds_read_b128 v[222:225], v141 offset:21504
	ds_read_b128 v[226:229], v141 offset:22528
	ds_read_b128 v[230:233], v141 offset:23552
	v_lshl_add_u64 v[162:163], s[20:21], 0, v[0:1]
	s_add_i32 s20, s88, 0x10000
	s_mov_b32 m0, s20
	s_nop 0
	s_nop 0
	global_load_lds_dwordx4 v[162:163], off
	v_lshl_add_u64 v[202:203], v[162:163], 0, s[64:65]
	s_add_i32 m0, s20, 0x2000
	s_add_i32 s20, s88, 0x14000
	global_load_lds_dwordx4 v[202:203], off
	v_lshl_add_u64 v[202:203], v[162:163], 0, s[72:73]
	s_mov_b32 m0, s20
	s_nop 0
	global_load_lds_dwordx4 v[202:203], off
	v_lshl_add_u64 v[202:203], v[162:163], 0, s[74:75]
	s_add_i32 m0, s20, 0x2000
	s_nop 0
	global_load_lds_dwordx4 v[202:203], off
	v_lshl_add_u64 v[202:203], s[68:69], 0, v[130:131]
	s_mov_b32 m0, s89
	v_lshl_add_u64 v[234:235], v[202:203], 0, s[64:65]
	global_load_lds_dwordx4 v[202:203], off
	s_mov_b32 m0, s90
	s_nop 0
	global_load_lds_dwordx4 v[234:235], off
	s_waitcnt vmcnt(8) lgkmcnt(0)
	s_barrier
	v_mfma_f32_16x16x32_bf16 v[62:65], v[134:137], v[190:193], v[62:65]
	v_mfma_f32_16x16x32_bf16 v[62:65], v[142:145], v[194:197], v[62:65]
	v_mfma_f32_16x16x32_bf16 v[58:61], v[146:149], v[190:193], v[58:61]
	v_mfma_f32_16x16x32_bf16 v[58:61], v[150:153], v[194:197], v[58:61]
	v_mfma_f32_16x16x32_bf16 v[46:49], v[134:137], v[198:201], v[46:49]
	v_mfma_f32_16x16x32_bf16 v[46:49], v[142:145], v[214:217], v[46:49]
	v_mfma_f32_16x16x32_bf16 v[42:45], v[146:149], v[198:201], v[42:45]
	v_mfma_f32_16x16x32_bf16 v[42:45], v[150:153], v[214:217], v[42:45]
	v_mfma_f32_16x16x32_bf16 v[30:33], v[134:137], v[218:221], v[30:33]
	v_mfma_f32_16x16x32_bf16 v[30:33], v[142:145], v[222:225], v[30:33]
	v_mfma_f32_16x16x32_bf16 v[26:29], v[146:149], v[218:221], v[26:29]
	v_mfma_f32_16x16x32_bf16 v[26:29], v[150:153], v[222:225], v[26:29]
	v_mfma_f32_16x16x32_bf16 v[14:17], v[134:137], v[226:229], v[14:17]
	v_mfma_f32_16x16x32_bf16 v[14:17], v[142:145], v[230:233], v[14:17]
	v_mfma_f32_16x16x32_bf16 v[10:13], v[146:149], v[226:229], v[10:13]
	v_mfma_f32_16x16x32_bf16 v[10:13], v[150:153], v[230:233], v[10:13]
	v_mfma_f32_16x16x32_bf16 v[54:57], v[154:157], v[190:193], v[54:57]
	v_mfma_f32_16x16x32_bf16 v[54:57], v[158:161], v[194:197], v[54:57]
	v_mfma_f32_16x16x32_bf16 v[50:53], v[182:185], v[190:193], v[50:53]
	v_mfma_f32_16x16x32_bf16 v[50:53], v[186:189], v[194:197], v[50:53]
	v_mfma_f32_16x16x32_bf16 v[38:41], v[154:157], v[198:201], v[38:41]
	v_mfma_f32_16x16x32_bf16 v[38:41], v[158:161], v[214:217], v[38:41]
	v_mfma_f32_16x16x32_bf16 v[34:37], v[182:185], v[198:201], v[34:37]
	v_mfma_f32_16x16x32_bf16 v[34:37], v[186:189], v[214:217], v[34:37]
	v_mfma_f32_16x16x32_bf16 v[22:25], v[154:157], v[218:221], v[22:25]
	v_mfma_f32_16x16x32_bf16 v[22:25], v[158:161], v[222:225], v[22:25]
	v_mfma_f32_16x16x32_bf16 v[18:21], v[182:185], v[218:221], v[18:21]
	v_mfma_f32_16x16x32_bf16 v[18:21], v[186:189], v[222:225], v[18:21]
	v_mfma_f32_16x16x32_bf16 v[6:9], v[154:157], v[226:229], v[6:9]
	v_mfma_f32_16x16x32_bf16 v[6:9], v[158:161], v[230:233], v[6:9]
	v_mfma_f32_16x16x32_bf16 v[2:5], v[182:185], v[226:229], v[2:5]
	v_mfma_f32_16x16x32_bf16 v[2:5], v[186:189], v[230:233], v[2:5]
	s_barrier
	ds_read_b128 v[134:137], v243 offset:32768
	ds_read_b128 v[142:145], v243 offset:33792
	ds_read_b128 v[146:149], v243 offset:34816
	ds_read_b128 v[150:153], v243 offset:35840
	ds_read_b128 v[154:157], v243 offset:49152
	ds_read_b128 v[158:161], v243 offset:50176
	ds_read_b128 v[182:185], v243 offset:51200
	ds_read_b128 v[186:189], v243 offset:52224
	ds_read_b128 v[190:193], v141 offset:32768
	ds_read_b128 v[194:197], v141 offset:33792
	ds_read_b128 v[198:201], v141 offset:34816
	ds_read_b128 v[214:217], v141 offset:35840
	ds_read_b128 v[218:221], v141 offset:36864
	ds_read_b128 v[222:225], v141 offset:37888
	ds_read_b128 v[226:229], v141 offset:38912
	ds_read_b128 v[230:233], v141 offset:39936
	s_mov_b32 m0, s91
	v_lshl_add_u64 v[234:235], v[202:203], 0, s[72:73]
	global_load_lds_dwordx4 v[234:235], off
	v_lshl_add_u64 v[234:235], v[202:203], 0, s[74:75]
	s_mov_b32 m0, s96
	s_nop 0
	global_load_lds_dwordx4 v[234:235], off
	s_waitcnt vmcnt(8) lgkmcnt(0)
	s_barrier
	v_mfma_f32_16x16x32_bf16 v[126:129], v[134:137], v[190:193], v[126:129]
	v_mfma_f32_16x16x32_bf16 v[126:129], v[142:145], v[194:197], v[126:129]
	v_mfma_f32_16x16x32_bf16 v[122:125], v[146:149], v[190:193], v[122:125]
	v_mfma_f32_16x16x32_bf16 v[122:125], v[150:153], v[194:197], v[122:125]
	v_mfma_f32_16x16x32_bf16 v[110:113], v[134:137], v[198:201], v[110:113]
	v_mfma_f32_16x16x32_bf16 v[110:113], v[142:145], v[214:217], v[110:113]
	v_mfma_f32_16x16x32_bf16 v[106:109], v[146:149], v[198:201], v[106:109]
	v_mfma_f32_16x16x32_bf16 v[106:109], v[150:153], v[214:217], v[106:109]
	v_mfma_f32_16x16x32_bf16 v[94:97], v[134:137], v[218:221], v[94:97]
	v_mfma_f32_16x16x32_bf16 v[94:97], v[142:145], v[222:225], v[94:97]
	v_mfma_f32_16x16x32_bf16 v[90:93], v[146:149], v[218:221], v[90:93]
	v_mfma_f32_16x16x32_bf16 v[90:93], v[150:153], v[222:225], v[90:93]
	v_mfma_f32_16x16x32_bf16 v[78:81], v[134:137], v[226:229], v[78:81]
	v_mfma_f32_16x16x32_bf16 v[78:81], v[142:145], v[230:233], v[78:81]
	v_mfma_f32_16x16x32_bf16 v[74:77], v[146:149], v[226:229], v[74:77]
	v_mfma_f32_16x16x32_bf16 v[74:77], v[150:153], v[230:233], v[74:77]
	v_mfma_f32_16x16x32_bf16 v[118:121], v[154:157], v[190:193], v[118:121]
	v_mfma_f32_16x16x32_bf16 v[118:121], v[158:161], v[194:197], v[118:121]
	v_mfma_f32_16x16x32_bf16 v[114:117], v[182:185], v[190:193], v[114:117]
	v_mfma_f32_16x16x32_bf16 v[114:117], v[186:189], v[194:197], v[114:117]
	v_mfma_f32_16x16x32_bf16 v[102:105], v[154:157], v[198:201], v[102:105]
	v_mfma_f32_16x16x32_bf16 v[102:105], v[158:161], v[214:217], v[102:105]
	v_mfma_f32_16x16x32_bf16 v[98:101], v[182:185], v[198:201], v[98:101]
	v_mfma_f32_16x16x32_bf16 v[98:101], v[186:189], v[214:217], v[98:101]
	v_mfma_f32_16x16x32_bf16 v[86:89], v[154:157], v[218:221], v[86:89]
	v_mfma_f32_16x16x32_bf16 v[86:89], v[158:161], v[222:225], v[86:89]
	v_mfma_f32_16x16x32_bf16 v[82:85], v[182:185], v[218:221], v[82:85]
	v_mfma_f32_16x16x32_bf16 v[82:85], v[186:189], v[222:225], v[82:85]
	v_mfma_f32_16x16x32_bf16 v[70:73], v[154:157], v[226:229], v[70:73]
	v_mfma_f32_16x16x32_bf16 v[70:73], v[158:161], v[230:233], v[70:73]
	v_mfma_f32_16x16x32_bf16 v[66:69], v[182:185], v[226:229], v[66:69]
	v_mfma_f32_16x16x32_bf16 v[66:69], v[186:189], v[230:233], v[66:69]
	s_barrier
	ds_read_b128 v[190:193], v141 offset:49152
	ds_read_b128 v[194:197], v141 offset:50176
	ds_read_b128 v[198:201], v141 offset:51200
	ds_read_b128 v[214:217], v141 offset:52224
	ds_read_b128 v[218:221], v141 offset:53248
	ds_read_b128 v[222:225], v141 offset:54272
	ds_read_b128 v[226:229], v141 offset:55296
	ds_read_b128 v[230:233], v141 offset:56320
	s_add_i32 s20, s88, 0x18000
	s_mov_b32 m0, s20
	v_lshl_add_u64 v[234:235], v[162:163], 0, s[34:35]
	global_load_lds_dwordx4 v[234:235], off
	v_lshl_add_u64 v[234:235], v[162:163], 0, s[80:81]
	s_add_i32 m0, s20, 0x2000
	s_add_i32 s20, s88, 0x1c000
	global_load_lds_dwordx4 v[234:235], off
	v_lshl_add_u64 v[234:235], v[162:163], 0, s[38:39]
	s_mov_b32 m0, s20
	v_lshl_add_u64 v[162:163], v[162:163], 0, s[86:87]
	global_load_lds_dwordx4 v[234:235], off
	s_add_i32 m0, s20, 0x2000
	s_nop 0
	global_load_lds_dwordx4 v[162:163], off
	v_lshl_add_u64 v[162:163], v[202:203], 0, s[34:35]
	s_mov_b32 m0, s97
	s_nop 0
	global_load_lds_dwordx4 v[162:163], off
	v_lshl_add_u64 v[162:163], v[202:203], 0, s[80:81]
	s_mov_b32 m0, s58
	s_nop 0
	global_load_lds_dwordx4 v[162:163], off
	s_waitcnt vmcnt(8) lgkmcnt(0)
	s_barrier
	v_mfma_f32_16x16x32_bf16 v[62:65], v[134:137], v[190:193], v[62:65]
	v_mfma_f32_16x16x32_bf16 v[62:65], v[142:145], v[194:197], v[62:65]
	v_mfma_f32_16x16x32_bf16 v[58:61], v[146:149], v[190:193], v[58:61]
	v_mfma_f32_16x16x32_bf16 v[58:61], v[150:153], v[194:197], v[58:61]
	v_mfma_f32_16x16x32_bf16 v[46:49], v[134:137], v[198:201], v[46:49]
	v_mfma_f32_16x16x32_bf16 v[46:49], v[142:145], v[214:217], v[46:49]
	v_mfma_f32_16x16x32_bf16 v[42:45], v[146:149], v[198:201], v[42:45]
	v_mfma_f32_16x16x32_bf16 v[42:45], v[150:153], v[214:217], v[42:45]
	v_mfma_f32_16x16x32_bf16 v[30:33], v[134:137], v[218:221], v[30:33]
	v_mfma_f32_16x16x32_bf16 v[30:33], v[142:145], v[222:225], v[30:33]
	v_mfma_f32_16x16x32_bf16 v[26:29], v[146:149], v[218:221], v[26:29]
	v_mfma_f32_16x16x32_bf16 v[26:29], v[150:153], v[222:225], v[26:29]
	v_mfma_f32_16x16x32_bf16 v[14:17], v[134:137], v[226:229], v[14:17]
	v_mfma_f32_16x16x32_bf16 v[14:17], v[142:145], v[230:233], v[14:17]
	v_mfma_f32_16x16x32_bf16 v[10:13], v[146:149], v[226:229], v[10:13]
	v_mfma_f32_16x16x32_bf16 v[10:13], v[150:153], v[230:233], v[10:13]
	s_add_i32 s84, s84, 2
	s_add_u32 s6, s6, 0x100
	s_addc_u32 s7, s7, 0
	s_add_u32 s49, s49, 0x100
	s_addc_u32 s51, s51, 0
	s_cmp_gt_u32 s84, 5
	v_mfma_f32_16x16x32_bf16 v[54:57], v[154:157], v[190:193], v[54:57]
	v_mfma_f32_16x16x32_bf16 v[54:57], v[158:161], v[194:197], v[54:57]
	v_mfma_f32_16x16x32_bf16 v[50:53], v[182:185], v[190:193], v[50:53]
	v_mfma_f32_16x16x32_bf16 v[50:53], v[186:189], v[194:197], v[50:53]
	v_mfma_f32_16x16x32_bf16 v[38:41], v[154:157], v[198:201], v[38:41]
	v_mfma_f32_16x16x32_bf16 v[38:41], v[158:161], v[214:217], v[38:41]
	v_mfma_f32_16x16x32_bf16 v[34:37], v[182:185], v[198:201], v[34:37]
	v_mfma_f32_16x16x32_bf16 v[34:37], v[186:189], v[214:217], v[34:37]
	v_mfma_f32_16x16x32_bf16 v[22:25], v[154:157], v[218:221], v[22:25]
	v_mfma_f32_16x16x32_bf16 v[22:25], v[158:161], v[222:225], v[22:25]
	v_mfma_f32_16x16x32_bf16 v[18:21], v[182:185], v[218:221], v[18:21]
	v_mfma_f32_16x16x32_bf16 v[18:21], v[186:189], v[222:225], v[18:21]
	v_mfma_f32_16x16x32_bf16 v[6:9], v[154:157], v[226:229], v[6:9]
	v_mfma_f32_16x16x32_bf16 v[6:9], v[158:161], v[230:233], v[6:9]
	v_mfma_f32_16x16x32_bf16 v[2:5], v[182:185], v[226:229], v[2:5]
	v_mfma_f32_16x16x32_bf16 v[2:5], v[186:189], v[230:233], v[2:5]
	s_barrier
	s_cbranch_scc0 .LBB0_604
	s_setprio 0
	s_and_b64 vcc, exec, s[52:53]
	s_cbranch_vccz .LBB0_607
	s_barrier

.LBB0_778:
	ds_read_b128 v[130:133], v243
	ds_read_b128 v[134:137], v243 offset:1024
	ds_read_b128 v[138:141], v243 offset:2048
	ds_read_b128 v[142:145], v243 offset:3072
	ds_read_b128 v[146:149], v243 offset:16384
	ds_read_b128 v[150:153], v243 offset:17408
	ds_read_b128 v[154:157], v243 offset:18432
	ds_read_b128 v[158:161], v243 offset:19456
	ds_read_b128 v[184:187], v196
	ds_read_b128 v[188:191], v196 offset:1024
	ds_read_b128 v[198:201], v196 offset:2048
	ds_read_b128 v[214:217], v196 offset:3072
	ds_read_b128 v[218:221], v196 offset:4096
	ds_read_b128 v[222:225], v196 offset:5120
	ds_read_b128 v[226:229], v196 offset:6144
	ds_read_b128 v[230:233], v196 offset:7168
	s_add_i32 m0, s43, 0xc000
	v_lshl_add_u64 v[202:203], s[76:77], 0, v[182:183]
	global_load_lds_dwordx4 v[202:203], off
	v_lshl_add_u64 v[202:203], v[202:203], 0, s[72:73]
	s_add_i32 m0, s43, 0xe000
	s_nop 0
	global_load_lds_dwordx4 v[202:203], off
	s_waitcnt vmcnt(8) lgkmcnt(0)
	s_barrier
	v_mfma_f32_16x16x32_bf16 v[126:129], v[130:133], v[184:187], v[126:129]
	v_mfma_f32_16x16x32_bf16 v[126:129], v[134:137], v[188:191], v[126:129]
	v_mfma_f32_16x16x32_bf16 v[122:125], v[138:141], v[184:187], v[122:125]
	v_mfma_f32_16x16x32_bf16 v[122:125], v[142:145], v[188:191], v[122:125]
	v_mfma_f32_16x16x32_bf16 v[110:113], v[130:133], v[198:201], v[110:113]
	v_mfma_f32_16x16x32_bf16 v[110:113], v[134:137], v[214:217], v[110:113]
	v_mfma_f32_16x16x32_bf16 v[106:109], v[138:141], v[198:201], v[106:109]
	v_mfma_f32_16x16x32_bf16 v[106:109], v[142:145], v[214:217], v[106:109]
	v_mfma_f32_16x16x32_bf16 v[94:97], v[130:133], v[218:221], v[94:97]
	v_mfma_f32_16x16x32_bf16 v[94:97], v[134:137], v[222:225], v[94:97]
	v_mfma_f32_16x16x32_bf16 v[90:93], v[138:141], v[218:221], v[90:93]
	v_mfma_f32_16x16x32_bf16 v[90:93], v[142:145], v[222:225], v[90:93]
	v_mfma_f32_16x16x32_bf16 v[78:81], v[130:133], v[226:229], v[78:81]
	v_mfma_f32_16x16x32_bf16 v[78:81], v[134:137], v[230:233], v[78:81]
	v_mfma_f32_16x16x32_bf16 v[74:77], v[138:141], v[226:229], v[74:77]
	v_mfma_f32_16x16x32_bf16 v[74:77], v[142:145], v[230:233], v[74:77]
	s_add_u32 s20, s76, 0xfffc0080
	s_addc_u32 s21, s77, -1
	s_cmp_eq_u32 vcc_hi, 12
	s_cselect_b32 s79, s61, s21
	s_cselect_b32 s78, s85, s20
	s_cselect_b32 s21, s59, vcc_lo
	s_cselect_b32 s20, s86, s87
	v_mfma_f32_16x16x32_bf16 v[118:121], v[146:149], v[184:187], v[118:121]
	v_mfma_f32_16x16x32_bf16 v[118:121], v[150:153], v[188:191], v[118:121]
	v_mfma_f32_16x16x32_bf16 v[114:117], v[154:157], v[184:187], v[114:117]
	v_mfma_f32_16x16x32_bf16 v[114:117], v[158:161], v[188:191], v[114:117]
	v_mfma_f32_16x16x32_bf16 v[102:105], v[146:149], v[198:201], v[102:105]
	v_mfma_f32_16x16x32_bf16 v[102:105], v[150:153], v[214:217], v[102:105]
	v_mfma_f32_16x16x32_bf16 v[98:101], v[154:157], v[198:201], v[98:101]
	v_mfma_f32_16x16x32_bf16 v[98:101], v[158:161], v[214:217], v[98:101]
	v_mfma_f32_16x16x32_bf16 v[86:89], v[146:149], v[218:221], v[86:89]
	v_mfma_f32_16x16x32_bf16 v[86:89], v[150:153], v[222:225], v[86:89]
	v_mfma_f32_16x16x32_bf16 v[82:85], v[154:157], v[218:221], v[82:85]
	v_mfma_f32_16x16x32_bf16 v[82:85], v[158:161], v[222:225], v[82:85]
	v_mfma_f32_16x16x32_bf16 v[70:73], v[146:149], v[226:229], v[70:73]
	v_mfma_f32_16x16x32_bf16 v[70:73], v[150:153], v[230:233], v[70:73]
	v_mfma_f32_16x16x32_bf16 v[66:69], v[154:157], v[226:229], v[66:69]
	v_mfma_f32_16x16x32_bf16 v[66:69], v[158:161], v[230:233], v[66:69]
	s_barrier
	ds_read_b128 v[184:187], v196 offset:16384
	ds_read_b128 v[188:191], v196 offset:17408
	ds_read_b128 v[198:201], v196 offset:18432
	ds_read_b128 v[214:217], v196 offset:19456
	ds_read_b128 v[218:221], v196 offset:20480
	ds_read_b128 v[222:225], v196 offset:21504
	ds_read_b128 v[226:229], v196 offset:22528
	ds_read_b128 v[230:233], v196 offset:23552
	v_lshl_add_u64 v[202:203], s[20:21], 0, v[0:1]
	s_add_i32 s20, s14, 0x10000
	s_mov_b32 m0, s20
	s_nop 0
	s_nop 0
	global_load_lds_dwordx4 v[202:203], off
	v_lshl_add_u64 v[234:235], v[202:203], 0, s[72:73]
	s_add_i32 m0, s20, 0x2000
	s_add_i32 s20, s14, 0x14000
	global_load_lds_dwordx4 v[234:235], off
	v_lshl_add_u64 v[234:235], v[202:203], 0, s[28:29]
	s_mov_b32 m0, s20
	s_nop 0
	global_load_lds_dwordx4 v[234:235], off
	v_lshl_add_u64 v[234:235], v[202:203], 0, s[82:83]
	s_add_i32 m0, s20, 0x2000
	s_nop 0
	global_load_lds_dwordx4 v[234:235], off
	v_lshl_add_u64 v[234:235], s[78:79], 0, v[162:163]
	s_mov_b32 m0, s43
	v_lshl_add_u64 v[236:237], v[234:235], 0, s[72:73]
	global_load_lds_dwordx4 v[234:235], off
	s_mov_b32 m0, s46
	s_nop 0
	global_load_lds_dwordx4 v[236:237], off
	s_waitcnt vmcnt(8) lgkmcnt(0)
	s_barrier
	v_mfma_f32_16x16x32_bf16 v[62:65], v[130:133], v[184:187], v[62:65]
	v_mfma_f32_16x16x32_bf16 v[62:65], v[134:137], v[188:191], v[62:65]
	v_mfma_f32_16x16x32_bf16 v[58:61], v[138:141], v[184:187], v[58:61]
	v_mfma_f32_16x16x32_bf16 v[58:61], v[142:145], v[188:191], v[58:61]
	v_mfma_f32_16x16x32_bf16 v[46:49], v[130:133], v[198:201], v[46:49]
	v_mfma_f32_16x16x32_bf16 v[46:49], v[134:137], v[214:217], v[46:49]
	v_mfma_f32_16x16x32_bf16 v[42:45], v[138:141], v[198:201], v[42:45]
	v_mfma_f32_16x16x32_bf16 v[42:45], v[142:145], v[214:217], v[42:45]
	v_mfma_f32_16x16x32_bf16 v[30:33], v[130:133], v[218:221], v[30:33]
	v_mfma_f32_16x16x32_bf16 v[30:33], v[134:137], v[222:225], v[30:33]
	v_mfma_f32_16x16x32_bf16 v[26:29], v[138:141], v[218:221], v[26:29]
	v_mfma_f32_16x16x32_bf16 v[26:29], v[142:145], v[222:225], v[26:29]
	v_mfma_f32_16x16x32_bf16 v[14:17], v[130:133], v[226:229], v[14:17]
	v_mfma_f32_16x16x32_bf16 v[14:17], v[134:137], v[230:233], v[14:17]
	v_mfma_f32_16x16x32_bf16 v[10:13], v[138:141], v[226:229], v[10:13]
	v_mfma_f32_16x16x32_bf16 v[10:13], v[142:145], v[230:233], v[10:13]
	v_mfma_f32_16x16x32_bf16 v[54:57], v[146:149], v[184:187], v[54:57]
	v_mfma_f32_16x16x32_bf16 v[54:57], v[150:153], v[188:191], v[54:57]
	v_mfma_f32_16x16x32_bf16 v[50:53], v[154:157], v[184:187], v[50:53]
	v_mfma_f32_16x16x32_bf16 v[50:53], v[158:161], v[188:191], v[50:53]
	v_mfma_f32_16x16x32_bf16 v[38:41], v[146:149], v[198:201], v[38:41]
	v_mfma_f32_16x16x32_bf16 v[38:41], v[150:153], v[214:217], v[38:41]
	v_mfma_f32_16x16x32_bf16 v[34:37], v[154:157], v[198:201], v[34:37]
	v_mfma_f32_16x16x32_bf16 v[34:37], v[158:161], v[214:217], v[34:37]
	v_mfma_f32_16x16x32_bf16 v[22:25], v[146:149], v[218:221], v[22:25]
	v_mfma_f32_16x16x32_bf16 v[22:25], v[150:153], v[222:225], v[22:25]
	v_mfma_f32_16x16x32_bf16 v[18:21], v[154:157], v[218:221], v[18:21]
	v_mfma_f32_16x16x32_bf16 v[18:21], v[158:161], v[222:225], v[18:21]
	v_mfma_f32_16x16x32_bf16 v[6:9], v[146:149], v[226:229], v[6:9]
	v_mfma_f32_16x16x32_bf16 v[6:9], v[150:153], v[230:233], v[6:9]
	v_mfma_f32_16x16x32_bf16 v[2:5], v[154:157], v[226:229], v[2:5]
	v_mfma_f32_16x16x32_bf16 v[2:5], v[158:161], v[230:233], v[2:5]
	s_barrier
	ds_read_b128 v[130:133], v243 offset:32768
	ds_read_b128 v[134:137], v243 offset:33792
	ds_read_b128 v[138:141], v243 offset:34816
	ds_read_b128 v[142:145], v243 offset:35840
	ds_read_b128 v[146:149], v243 offset:49152
	ds_read_b128 v[150:153], v243 offset:50176
	ds_read_b128 v[154:157], v243 offset:51200
	ds_read_b128 v[158:161], v243 offset:52224
	ds_read_b128 v[184:187], v196 offset:32768
	ds_read_b128 v[188:191], v196 offset:33792
	ds_read_b128 v[198:201], v196 offset:34816
	ds_read_b128 v[214:217], v196 offset:35840
	ds_read_b128 v[218:221], v196 offset:36864
	ds_read_b128 v[222:225], v196 offset:37888
	ds_read_b128 v[226:229], v196 offset:38912
	ds_read_b128 v[230:233], v196 offset:39936
	s_mov_b32 m0, s47
	v_lshl_add_u64 v[236:237], v[234:235], 0, s[28:29]
	global_load_lds_dwordx4 v[236:237], off
	v_lshl_add_u64 v[236:237], v[234:235], 0, s[82:83]
	s_mov_b32 m0, s88
	s_nop 0
	global_load_lds_dwordx4 v[236:237], off
	s_waitcnt vmcnt(8) lgkmcnt(0)
	s_barrier
	v_mfma_f32_16x16x32_bf16 v[126:129], v[130:133], v[184:187], v[126:129]
	v_mfma_f32_16x16x32_bf16 v[126:129], v[134:137], v[188:191], v[126:129]
	v_mfma_f32_16x16x32_bf16 v[122:125], v[138:141], v[184:187], v[122:125]
	v_mfma_f32_16x16x32_bf16 v[122:125], v[142:145], v[188:191], v[122:125]
	v_mfma_f32_16x16x32_bf16 v[110:113], v[130:133], v[198:201], v[110:113]
	v_mfma_f32_16x16x32_bf16 v[110:113], v[134:137], v[214:217], v[110:113]
	v_mfma_f32_16x16x32_bf16 v[106:109], v[138:141], v[198:201], v[106:109]
	v_mfma_f32_16x16x32_bf16 v[106:109], v[142:145], v[214:217], v[106:109]
	v_mfma_f32_16x16x32_bf16 v[94:97], v[130:133], v[218:221], v[94:97]
	v_mfma_f32_16x16x32_bf16 v[94:97], v[134:137], v[222:225], v[94:97]
	v_mfma_f32_16x16x32_bf16 v[90:93], v[138:141], v[218:221], v[90:93]
	v_mfma_f32_16x16x32_bf16 v[90:93], v[142:145], v[222:225], v[90:93]
	v_mfma_f32_16x16x32_bf16 v[78:81], v[130:133], v[226:229], v[78:81]
	v_mfma_f32_16x16x32_bf16 v[78:81], v[134:137], v[230:233], v[78:81]
	v_mfma_f32_16x16x32_bf16 v[74:77], v[138:141], v[226:229], v[74:77]
	v_mfma_f32_16x16x32_bf16 v[74:77], v[142:145], v[230:233], v[74:77]
	v_mfma_f32_16x16x32_bf16 v[118:121], v[146:149], v[184:187], v[118:121]
	v_mfma_f32_16x16x32_bf16 v[118:121], v[150:153], v[188:191], v[118:121]
	v_mfma_f32_16x16x32_bf16 v[114:117], v[154:157], v[184:187], v[114:117]
	v_mfma_f32_16x16x32_bf16 v[114:117], v[158:161], v[188:191], v[114:117]
	v_mfma_f32_16x16x32_bf16 v[102:105], v[146:149], v[198:201], v[102:105]
	v_mfma_f32_16x16x32_bf16 v[102:105], v[150:153], v[214:217], v[102:105]
	v_mfma_f32_16x16x32_bf16 v[98:101], v[154:157], v[198:201], v[98:101]
	v_mfma_f32_16x16x32_bf16 v[98:101], v[158:161], v[214:217], v[98:101]
	v_mfma_f32_16x16x32_bf16 v[86:89], v[146:149], v[218:221], v[86:89]
	v_mfma_f32_16x16x32_bf16 v[86:89], v[150:153], v[222:225], v[86:89]
	v_mfma_f32_16x16x32_bf16 v[82:85], v[154:157], v[218:221], v[82:85]
	v_mfma_f32_16x16x32_bf16 v[82:85], v[158:161], v[222:225], v[82:85]
	v_mfma_f32_16x16x32_bf16 v[70:73], v[146:149], v[226:229], v[70:73]
	v_mfma_f32_16x16x32_bf16 v[70:73], v[150:153], v[230:233], v[70:73]
	v_mfma_f32_16x16x32_bf16 v[66:69], v[154:157], v[226:229], v[66:69]
	v_mfma_f32_16x16x32_bf16 v[66:69], v[158:161], v[230:233], v[66:69]
	s_barrier
	ds_read_b128 v[184:187], v196 offset:49152
	ds_read_b128 v[188:191], v196 offset:50176
	ds_read_b128 v[198:201], v196 offset:51200
	ds_read_b128 v[214:217], v196 offset:52224
	ds_read_b128 v[218:221], v196 offset:53248
	ds_read_b128 v[222:225], v196 offset:54272
	ds_read_b128 v[226:229], v196 offset:55296
	ds_read_b128 v[230:233], v196 offset:56320
	s_add_i32 s20, s14, 0x18000
	s_mov_b32 m0, s20
	v_lshl_add_u64 v[236:237], v[202:203], 0, s[34:35]
	global_load_lds_dwordx4 v[236:237], off
	v_lshl_add_u64 v[236:237], v[202:203], 0, s[38:39]
	s_add_i32 m0, s20, 0x2000
	s_add_i32 s20, s14, 0x1c000
	global_load_lds_dwordx4 v[236:237], off
	v_lshl_add_u64 v[236:237], v[202:203], 0, s[44:45]
	s_mov_b32 m0, s20
	v_lshl_add_u64 v[202:203], v[202:203], 0, s[10:11]
	global_load_lds_dwordx4 v[236:237], off
	s_add_i32 m0, s20, 0x2000
	s_nop 0
	global_load_lds_dwordx4 v[202:203], off
	v_lshl_add_u64 v[202:203], v[234:235], 0, s[34:35]
	s_mov_b32 m0, s89
	s_nop 0
	global_load_lds_dwordx4 v[202:203], off
	v_lshl_add_u64 v[202:203], v[234:235], 0, s[38:39]
	s_mov_b32 m0, s90
	s_nop 0
	global_load_lds_dwordx4 v[202:203], off
	s_waitcnt vmcnt(8) lgkmcnt(0)
	s_barrier
	v_mfma_f32_16x16x32_bf16 v[62:65], v[130:133], v[184:187], v[62:65]
	v_mfma_f32_16x16x32_bf16 v[62:65], v[134:137], v[188:191], v[62:65]
	v_mfma_f32_16x16x32_bf16 v[58:61], v[138:141], v[184:187], v[58:61]
	v_mfma_f32_16x16x32_bf16 v[58:61], v[142:145], v[188:191], v[58:61]
	v_mfma_f32_16x16x32_bf16 v[46:49], v[130:133], v[198:201], v[46:49]
	v_mfma_f32_16x16x32_bf16 v[46:49], v[134:137], v[214:217], v[46:49]
	v_mfma_f32_16x16x32_bf16 v[42:45], v[138:141], v[198:201], v[42:45]
	v_mfma_f32_16x16x32_bf16 v[42:45], v[142:145], v[214:217], v[42:45]
	v_mfma_f32_16x16x32_bf16 v[30:33], v[130:133], v[218:221], v[30:33]
	v_mfma_f32_16x16x32_bf16 v[30:33], v[134:137], v[222:225], v[30:33]
	v_mfma_f32_16x16x32_bf16 v[26:29], v[138:141], v[218:221], v[26:29]
	v_mfma_f32_16x16x32_bf16 v[26:29], v[142:145], v[222:225], v[26:29]
	v_mfma_f32_16x16x32_bf16 v[14:17], v[130:133], v[226:229], v[14:17]
	v_mfma_f32_16x16x32_bf16 v[14:17], v[134:137], v[230:233], v[14:17]
	v_mfma_f32_16x16x32_bf16 v[10:13], v[138:141], v[226:229], v[10:13]
	v_mfma_f32_16x16x32_bf16 v[10:13], v[142:145], v[230:233], v[10:13]
	s_add_i32 vcc_hi, vcc_hi, 2
	s_add_u32 s76, s76, 0x100
	s_addc_u32 s77, s77, 0
	s_add_u32 s87, s87, 0x100
	s_addc_u32 vcc_lo, vcc_lo, 0
	s_cmp_gt_u32 vcc_hi, 13
	v_mfma_f32_16x16x32_bf16 v[54:57], v[146:149], v[184:187], v[54:57]
	v_mfma_f32_16x16x32_bf16 v[54:57], v[150:153], v[188:191], v[54:57]
	v_mfma_f32_16x16x32_bf16 v[50:53], v[154:157], v[184:187], v[50:53]
	v_mfma_f32_16x16x32_bf16 v[50:53], v[158:161], v[188:191], v[50:53]
	v_mfma_f32_16x16x32_bf16 v[38:41], v[146:149], v[198:201], v[38:41]
	v_mfma_f32_16x16x32_bf16 v[38:41], v[150:153], v[214:217], v[38:41]
	v_mfma_f32_16x16x32_bf16 v[34:37], v[154:157], v[198:201], v[34:37]
	v_mfma_f32_16x16x32_bf16 v[34:37], v[158:161], v[214:217], v[34:37]
	v_mfma_f32_16x16x32_bf16 v[22:25], v[146:149], v[218:221], v[22:25]
	v_mfma_f32_16x16x32_bf16 v[22:25], v[150:153], v[222:225], v[22:25]
	v_mfma_f32_16x16x32_bf16 v[18:21], v[154:157], v[218:221], v[18:21]
	v_mfma_f32_16x16x32_bf16 v[18:21], v[158:161], v[222:225], v[18:21]
	v_mfma_f32_16x16x32_bf16 v[6:9], v[146:149], v[226:229], v[6:9]
	v_mfma_f32_16x16x32_bf16 v[6:9], v[150:153], v[230:233], v[6:9]
	v_mfma_f32_16x16x32_bf16 v[2:5], v[154:157], v[226:229], v[2:5]
	v_mfma_f32_16x16x32_bf16 v[2:5], v[158:161], v[230:233], v[2:5]
	s_barrier
	s_cbranch_scc0 .LBB0_778
	s_setprio 0
	s_and_b64 vcc, exec, s[50:51]
	s_cbranch_vccz .LBB0_781
	s_barrier

.LBB0_850:
	ds_read_b128 v[138:141], v243
	ds_read_b128 v[146:149], v243 offset:1024
	ds_read_b128 v[150:153], v243 offset:2048
	ds_read_b128 v[158:161], v243 offset:3072
	ds_read_b128 v[182:185], v243 offset:16384
	ds_read_b128 v[186:189], v243 offset:17408
	ds_read_b128 v[190:193], v243 offset:18432
	ds_read_b128 v[194:197], v243 offset:19456
	ds_read_b128 v[198:201], v157
	ds_read_b128 v[214:217], v157 offset:1024
	ds_read_b128 v[218:221], v157 offset:2048
	ds_read_b128 v[222:225], v157 offset:3072
	ds_read_b128 v[226:229], v157 offset:4096
	ds_read_b128 v[230:233], v157 offset:5120
	ds_read_b128 v[234:237], v157 offset:6144
	ds_read_b128 v[238:241], v157 offset:7168
	s_add_i32 m0, s15, 0xc000
	v_lshl_add_u64 v[142:143], s[56:57], 0, v[136:137]
	global_load_lds_dwordx4 v[142:143], off
	v_lshl_add_u64 v[142:143], v[142:143], 0, s[72:73]
	s_add_i32 m0, s15, 0xe000
	s_nop 0
	global_load_lds_dwordx4 v[142:143], off
	s_waitcnt vmcnt(8) lgkmcnt(0)
	s_barrier
	v_mfma_f32_16x16x32_bf16 v[126:129], v[138:141], v[198:201], v[126:129]
	v_mfma_f32_16x16x32_bf16 v[126:129], v[146:149], v[214:217], v[126:129]
	v_mfma_f32_16x16x32_bf16 v[122:125], v[150:153], v[198:201], v[122:125]
	v_mfma_f32_16x16x32_bf16 v[122:125], v[158:161], v[214:217], v[122:125]
	v_mfma_f32_16x16x32_bf16 v[110:113], v[138:141], v[218:221], v[110:113]
	v_mfma_f32_16x16x32_bf16 v[110:113], v[146:149], v[222:225], v[110:113]
	v_mfma_f32_16x16x32_bf16 v[106:109], v[150:153], v[218:221], v[106:109]
	v_mfma_f32_16x16x32_bf16 v[106:109], v[158:161], v[222:225], v[106:109]
	v_mfma_f32_16x16x32_bf16 v[94:97], v[138:141], v[226:229], v[94:97]
	v_mfma_f32_16x16x32_bf16 v[94:97], v[146:149], v[230:233], v[94:97]
	v_mfma_f32_16x16x32_bf16 v[90:93], v[150:153], v[226:229], v[90:93]
	v_mfma_f32_16x16x32_bf16 v[90:93], v[158:161], v[230:233], v[90:93]
	v_mfma_f32_16x16x32_bf16 v[78:81], v[138:141], v[234:237], v[78:81]
	v_mfma_f32_16x16x32_bf16 v[78:81], v[146:149], v[238:241], v[78:81]
	v_mfma_f32_16x16x32_bf16 v[74:77], v[150:153], v[234:237], v[74:77]
	v_mfma_f32_16x16x32_bf16 v[74:77], v[158:161], v[238:241], v[74:77]
	s_add_u32 s20, s56, 0xfffc0080
	s_addc_u32 s21, s57, -1
	s_cmp_eq_u32 s91, 12
	s_cselect_b32 s59, s76, s21
	s_cselect_b32 s58, s77, s20
	s_cselect_b32 s21, s69, s87
	s_cselect_b32 s20, s79, s86
	v_mfma_f32_16x16x32_bf16 v[118:121], v[182:185], v[198:201], v[118:121]
	v_mfma_f32_16x16x32_bf16 v[118:121], v[186:189], v[214:217], v[118:121]
	v_mfma_f32_16x16x32_bf16 v[114:117], v[190:193], v[198:201], v[114:117]
	v_mfma_f32_16x16x32_bf16 v[114:117], v[194:197], v[214:217], v[114:117]
	v_mfma_f32_16x16x32_bf16 v[102:105], v[182:185], v[218:221], v[102:105]
	v_mfma_f32_16x16x32_bf16 v[102:105], v[186:189], v[222:225], v[102:105]
	v_mfma_f32_16x16x32_bf16 v[98:101], v[190:193], v[218:221], v[98:101]
	v_mfma_f32_16x16x32_bf16 v[98:101], v[194:197], v[222:225], v[98:101]
	v_mfma_f32_16x16x32_bf16 v[86:89], v[182:185], v[226:229], v[86:89]
	v_mfma_f32_16x16x32_bf16 v[86:89], v[186:189], v[230:233], v[86:89]
	v_mfma_f32_16x16x32_bf16 v[82:85], v[190:193], v[226:229], v[82:85]
	v_mfma_f32_16x16x32_bf16 v[82:85], v[194:197], v[230:233], v[82:85]
	v_mfma_f32_16x16x32_bf16 v[70:73], v[182:185], v[234:237], v[70:73]
	v_mfma_f32_16x16x32_bf16 v[70:73], v[186:189], v[238:241], v[70:73]
	v_mfma_f32_16x16x32_bf16 v[66:69], v[190:193], v[234:237], v[66:69]
	v_mfma_f32_16x16x32_bf16 v[66:69], v[194:197], v[238:241], v[66:69]
	s_barrier
	ds_read_b128 v[198:201], v157 offset:16384
	ds_read_b128 v[214:217], v157 offset:17408
	ds_read_b128 v[218:221], v157 offset:18432
	ds_read_b128 v[222:225], v157 offset:19456
	ds_read_b128 v[226:229], v157 offset:20480
	ds_read_b128 v[230:233], v157 offset:21504
	ds_read_b128 v[234:237], v157 offset:22528
	ds_read_b128 v[238:241], v157 offset:23552
	v_lshl_add_u64 v[142:143], s[20:21], 0, v[130:131]
	s_add_i32 s20, s14, 0x10000
	s_mov_b32 m0, s20
	s_nop 0
	s_nop 0
	global_load_lds_dwordx4 v[142:143], off
	v_lshl_add_u64 v[162:163], v[142:143], 0, s[72:73]
	s_add_i32 m0, s20, 0x2000
	s_add_i32 s20, s14, 0x14000
	global_load_lds_dwordx4 v[162:163], off
	v_lshl_add_u64 v[162:163], v[142:143], 0, s[28:29]
	s_mov_b32 m0, s20
	s_nop 0
	global_load_lds_dwordx4 v[162:163], off
	v_lshl_add_u64 v[162:163], v[142:143], 0, s[82:83]
	s_add_i32 m0, s20, 0x2000
	s_nop 0
	global_load_lds_dwordx4 v[162:163], off
	v_lshl_add_u64 v[162:163], s[58:59], 0, v[132:133]
	s_mov_b32 m0, s15
	v_lshl_add_u64 v[202:203], v[162:163], 0, s[72:73]
	global_load_lds_dwordx4 v[162:163], off
	s_mov_b32 m0, s42
	s_nop 0
	global_load_lds_dwordx4 v[202:203], off
	s_waitcnt vmcnt(8) lgkmcnt(0)
	s_barrier
	v_mfma_f32_16x16x32_bf16 v[62:65], v[138:141], v[198:201], v[62:65]
	v_mfma_f32_16x16x32_bf16 v[62:65], v[146:149], v[214:217], v[62:65]
	v_mfma_f32_16x16x32_bf16 v[58:61], v[150:153], v[198:201], v[58:61]
	v_mfma_f32_16x16x32_bf16 v[58:61], v[158:161], v[214:217], v[58:61]
	v_mfma_f32_16x16x32_bf16 v[46:49], v[138:141], v[218:221], v[46:49]
	v_mfma_f32_16x16x32_bf16 v[46:49], v[146:149], v[222:225], v[46:49]
	v_mfma_f32_16x16x32_bf16 v[42:45], v[150:153], v[218:221], v[42:45]
	v_mfma_f32_16x16x32_bf16 v[42:45], v[158:161], v[222:225], v[42:45]
	v_mfma_f32_16x16x32_bf16 v[30:33], v[138:141], v[226:229], v[30:33]
	v_mfma_f32_16x16x32_bf16 v[30:33], v[146:149], v[230:233], v[30:33]
	v_mfma_f32_16x16x32_bf16 v[26:29], v[150:153], v[226:229], v[26:29]
	v_mfma_f32_16x16x32_bf16 v[26:29], v[158:161], v[230:233], v[26:29]
	v_mfma_f32_16x16x32_bf16 v[14:17], v[138:141], v[234:237], v[14:17]
	v_mfma_f32_16x16x32_bf16 v[14:17], v[146:149], v[238:241], v[14:17]
	v_mfma_f32_16x16x32_bf16 v[10:13], v[150:153], v[234:237], v[10:13]
	v_mfma_f32_16x16x32_bf16 v[10:13], v[158:161], v[238:241], v[10:13]
	v_mfma_f32_16x16x32_bf16 v[54:57], v[182:185], v[198:201], v[54:57]
	v_mfma_f32_16x16x32_bf16 v[54:57], v[186:189], v[214:217], v[54:57]
	v_mfma_f32_16x16x32_bf16 v[50:53], v[190:193], v[198:201], v[50:53]
	v_mfma_f32_16x16x32_bf16 v[50:53], v[194:197], v[214:217], v[50:53]
	v_mfma_f32_16x16x32_bf16 v[38:41], v[182:185], v[218:221], v[38:41]
	v_mfma_f32_16x16x32_bf16 v[38:41], v[186:189], v[222:225], v[38:41]
	v_mfma_f32_16x16x32_bf16 v[34:37], v[190:193], v[218:221], v[34:37]
	v_mfma_f32_16x16x32_bf16 v[34:37], v[194:197], v[222:225], v[34:37]
	v_mfma_f32_16x16x32_bf16 v[22:25], v[182:185], v[226:229], v[22:25]
	v_mfma_f32_16x16x32_bf16 v[22:25], v[186:189], v[230:233], v[22:25]
	v_mfma_f32_16x16x32_bf16 v[18:21], v[190:193], v[226:229], v[18:21]
	v_mfma_f32_16x16x32_bf16 v[18:21], v[194:197], v[230:233], v[18:21]
	v_mfma_f32_16x16x32_bf16 v[6:9], v[182:185], v[234:237], v[6:9]
	v_mfma_f32_16x16x32_bf16 v[6:9], v[186:189], v[238:241], v[6:9]
	v_mfma_f32_16x16x32_bf16 v[2:5], v[190:193], v[234:237], v[2:5]
	v_mfma_f32_16x16x32_bf16 v[2:5], v[194:197], v[238:241], v[2:5]
	s_barrier
	ds_read_b128 v[138:141], v243 offset:32768
	ds_read_b128 v[146:149], v243 offset:33792
	ds_read_b128 v[150:153], v243 offset:34816
	ds_read_b128 v[158:161], v243 offset:35840
	ds_read_b128 v[182:185], v243 offset:49152
	ds_read_b128 v[186:189], v243 offset:50176
	ds_read_b128 v[190:193], v243 offset:51200
	ds_read_b128 v[194:197], v243 offset:52224
	ds_read_b128 v[198:201], v157 offset:32768
	ds_read_b128 v[214:217], v157 offset:33792
	ds_read_b128 v[218:221], v157 offset:34816
	ds_read_b128 v[222:225], v157 offset:35840
	ds_read_b128 v[226:229], v157 offset:36864
	ds_read_b128 v[230:233], v157 offset:37888
	ds_read_b128 v[234:237], v157 offset:38912
	ds_read_b128 v[238:241], v157 offset:39936
	s_mov_b32 m0, s43
	v_lshl_add_u64 v[202:203], v[162:163], 0, s[28:29]
	global_load_lds_dwordx4 v[202:203], off
	v_lshl_add_u64 v[202:203], v[162:163], 0, s[82:83]
	s_mov_b32 m0, s46
	s_nop 0
	global_load_lds_dwordx4 v[202:203], off
	s_waitcnt vmcnt(8) lgkmcnt(0)
	s_barrier
	v_mfma_f32_16x16x32_bf16 v[126:129], v[138:141], v[198:201], v[126:129]
	v_mfma_f32_16x16x32_bf16 v[126:129], v[146:149], v[214:217], v[126:129]
	v_mfma_f32_16x16x32_bf16 v[122:125], v[150:153], v[198:201], v[122:125]
	v_mfma_f32_16x16x32_bf16 v[122:125], v[158:161], v[214:217], v[122:125]
	v_mfma_f32_16x16x32_bf16 v[110:113], v[138:141], v[218:221], v[110:113]
	v_mfma_f32_16x16x32_bf16 v[110:113], v[146:149], v[222:225], v[110:113]
	v_mfma_f32_16x16x32_bf16 v[106:109], v[150:153], v[218:221], v[106:109]
	v_mfma_f32_16x16x32_bf16 v[106:109], v[158:161], v[222:225], v[106:109]
	v_mfma_f32_16x16x32_bf16 v[94:97], v[138:141], v[226:229], v[94:97]
	v_mfma_f32_16x16x32_bf16 v[94:97], v[146:149], v[230:233], v[94:97]
	v_mfma_f32_16x16x32_bf16 v[90:93], v[150:153], v[226:229], v[90:93]
	v_mfma_f32_16x16x32_bf16 v[90:93], v[158:161], v[230:233], v[90:93]
	v_mfma_f32_16x16x32_bf16 v[78:81], v[138:141], v[234:237], v[78:81]
	v_mfma_f32_16x16x32_bf16 v[78:81], v[146:149], v[238:241], v[78:81]
	v_mfma_f32_16x16x32_bf16 v[74:77], v[150:153], v[234:237], v[74:77]
	v_mfma_f32_16x16x32_bf16 v[74:77], v[158:161], v[238:241], v[74:77]
	v_mfma_f32_16x16x32_bf16 v[118:121], v[182:185], v[198:201], v[118:121]
	v_mfma_f32_16x16x32_bf16 v[118:121], v[186:189], v[214:217], v[118:121]
	v_mfma_f32_16x16x32_bf16 v[114:117], v[190:193], v[198:201], v[114:117]
	v_mfma_f32_16x16x32_bf16 v[114:117], v[194:197], v[214:217], v[114:117]
	v_mfma_f32_16x16x32_bf16 v[102:105], v[182:185], v[218:221], v[102:105]
	v_mfma_f32_16x16x32_bf16 v[102:105], v[186:189], v[222:225], v[102:105]
	v_mfma_f32_16x16x32_bf16 v[98:101], v[190:193], v[218:221], v[98:101]
	v_mfma_f32_16x16x32_bf16 v[98:101], v[194:197], v[222:225], v[98:101]
	v_mfma_f32_16x16x32_bf16 v[86:89], v[182:185], v[226:229], v[86:89]
	v_mfma_f32_16x16x32_bf16 v[86:89], v[186:189], v[230:233], v[86:89]
	v_mfma_f32_16x16x32_bf16 v[82:85], v[190:193], v[226:229], v[82:85]
	v_mfma_f32_16x16x32_bf16 v[82:85], v[194:197], v[230:233], v[82:85]
	v_mfma_f32_16x16x32_bf16 v[70:73], v[182:185], v[234:237], v[70:73]
	v_mfma_f32_16x16x32_bf16 v[70:73], v[186:189], v[238:241], v[70:73]
	v_mfma_f32_16x16x32_bf16 v[66:69], v[190:193], v[234:237], v[66:69]
	v_mfma_f32_16x16x32_bf16 v[66:69], v[194:197], v[238:241], v[66:69]
	s_barrier
	ds_read_b128 v[198:201], v157 offset:49152
	ds_read_b128 v[214:217], v157 offset:50176
	ds_read_b128 v[218:221], v157 offset:51200
	ds_read_b128 v[222:225], v157 offset:52224
	ds_read_b128 v[226:229], v157 offset:53248
	ds_read_b128 v[230:233], v157 offset:54272
	ds_read_b128 v[234:237], v157 offset:55296
	ds_read_b128 v[238:241], v157 offset:56320
	s_add_i32 s20, s14, 0x18000
	s_mov_b32 m0, s20
	v_lshl_add_u64 v[202:203], v[142:143], 0, s[34:35]
	global_load_lds_dwordx4 v[202:203], off
	v_lshl_add_u64 v[202:203], v[142:143], 0, s[38:39]
	s_add_i32 m0, s20, 0x2000
	s_add_i32 s20, s14, 0x1c000
	global_load_lds_dwordx4 v[202:203], off
	v_lshl_add_u64 v[202:203], v[142:143], 0, s[44:45]
	s_mov_b32 m0, s20
	v_lshl_add_u64 v[142:143], v[142:143], 0, s[10:11]
	global_load_lds_dwordx4 v[202:203], off
	s_add_i32 m0, s20, 0x2000
	s_nop 0
	global_load_lds_dwordx4 v[142:143], off
	v_lshl_add_u64 v[142:143], v[162:163], 0, s[34:35]
	s_mov_b32 m0, s47
	s_nop 0
	global_load_lds_dwordx4 v[142:143], off
	v_lshl_add_u64 v[142:143], v[162:163], 0, s[38:39]
	s_mov_b32 m0, s96
	s_nop 0
	global_load_lds_dwordx4 v[142:143], off
	s_waitcnt vmcnt(8) lgkmcnt(0)
	s_barrier
	v_mfma_f32_16x16x32_bf16 v[62:65], v[138:141], v[198:201], v[62:65]
	v_mfma_f32_16x16x32_bf16 v[62:65], v[146:149], v[214:217], v[62:65]
	v_mfma_f32_16x16x32_bf16 v[58:61], v[150:153], v[198:201], v[58:61]
	v_mfma_f32_16x16x32_bf16 v[58:61], v[158:161], v[214:217], v[58:61]
	v_mfma_f32_16x16x32_bf16 v[46:49], v[138:141], v[218:221], v[46:49]
	v_mfma_f32_16x16x32_bf16 v[46:49], v[146:149], v[222:225], v[46:49]
	v_mfma_f32_16x16x32_bf16 v[42:45], v[150:153], v[218:221], v[42:45]
	v_mfma_f32_16x16x32_bf16 v[42:45], v[158:161], v[222:225], v[42:45]
	v_mfma_f32_16x16x32_bf16 v[30:33], v[138:141], v[226:229], v[30:33]
	v_mfma_f32_16x16x32_bf16 v[30:33], v[146:149], v[230:233], v[30:33]
	v_mfma_f32_16x16x32_bf16 v[26:29], v[150:153], v[226:229], v[26:29]
	v_mfma_f32_16x16x32_bf16 v[26:29], v[158:161], v[230:233], v[26:29]
	v_mfma_f32_16x16x32_bf16 v[14:17], v[138:141], v[234:237], v[14:17]
	v_mfma_f32_16x16x32_bf16 v[14:17], v[146:149], v[238:241], v[14:17]
	v_mfma_f32_16x16x32_bf16 v[10:13], v[150:153], v[234:237], v[10:13]
	v_mfma_f32_16x16x32_bf16 v[10:13], v[158:161], v[238:241], v[10:13]
	s_add_i32 s91, s91, 2
	s_add_u32 s56, s56, 0x100
	s_addc_u32 s57, s57, 0
	s_add_u32 s86, s86, 0x100
	s_addc_u32 s87, s87, 0
	s_cmp_gt_u32 s91, 13
	v_mfma_f32_16x16x32_bf16 v[54:57], v[182:185], v[198:201], v[54:57]
	v_mfma_f32_16x16x32_bf16 v[54:57], v[186:189], v[214:217], v[54:57]
	v_mfma_f32_16x16x32_bf16 v[50:53], v[190:193], v[198:201], v[50:53]
	v_mfma_f32_16x16x32_bf16 v[50:53], v[194:197], v[214:217], v[50:53]
	v_mfma_f32_16x16x32_bf16 v[38:41], v[182:185], v[218:221], v[38:41]
	v_mfma_f32_16x16x32_bf16 v[38:41], v[186:189], v[222:225], v[38:41]
	v_mfma_f32_16x16x32_bf16 v[34:37], v[190:193], v[218:221], v[34:37]
	v_mfma_f32_16x16x32_bf16 v[34:37], v[194:197], v[222:225], v[34:37]
	v_mfma_f32_16x16x32_bf16 v[22:25], v[182:185], v[226:229], v[22:25]
	v_mfma_f32_16x16x32_bf16 v[22:25], v[186:189], v[230:233], v[22:25]
	v_mfma_f32_16x16x32_bf16 v[18:21], v[190:193], v[226:229], v[18:21]
	v_mfma_f32_16x16x32_bf16 v[18:21], v[194:197], v[230:233], v[18:21]
	v_mfma_f32_16x16x32_bf16 v[6:9], v[182:185], v[234:237], v[6:9]
	v_mfma_f32_16x16x32_bf16 v[6:9], v[186:189], v[238:241], v[6:9]
	v_mfma_f32_16x16x32_bf16 v[2:5], v[190:193], v[234:237], v[2:5]
	v_mfma_f32_16x16x32_bf16 v[2:5], v[194:197], v[238:241], v[2:5]
	s_barrier
	s_cbranch_scc0 .LBB0_850
	s_setprio 0
	s_and_b64 vcc, exec, s[62:63]
	s_cbranch_vccz .LBB0_853
	s_barrier
